# P1 K-loop: static s_setprio 1 for waves 4-7 (test)
# speedup vs baseline: 1.0053x; 1.0053x over previous
;     ...
;   const int srow = tid >> 3, skc = tid & 7;
;   const u16* Ag = A + (size_t)(m0 + srow) * K + skc * 8;
;   const u16* Bg[4];
; #pragma unroll
;   for (int i = 0; i < 4; ++i) { int n = n0 + srow + 64 * i; n = n < nmax ? n : nmax - 1; Bg[i] = Bt + (size_t)n * K + skc * 8; }
;   const int nk = nk_override ? nk_override : K / 64;
; #pragma unroll
;   for (int i = 0; i < 4; ++i) { ra[i] = *(const u32x4*)(Ag + (size_t)(64 * i) * K); rb[i] = *(const u32x4*)(Bg[i]); }
; #pragma unroll
;   for (int i = 0; i < 4; ++i) { *(u32x4*)(As0 + (srow + 64 * i) * LD + skc * 8) = ra[i]; *(u32x4*)(Bs0 + (srow + 64 * i) * LD + skc * 8) = rb[i]; }
;   if (nk > 1) {
; #pragma unroll
;     for (int i = 0; i < 4; ++i) { ra[i] = *(const u32x4*)(Ag + (size_t)(64 * i) * K + 64); rb[i] = *(const u32x4*)(Bg[i] + 64); }
;   }
;   for (int kt = 0; kt < nk; ++kt) {
;     __syncthreads();
.LBB0_107:
	s_lshl_b32 s34, s34, 1
	s_add_i32 s34, s34, s40
	s_and_b32 s30, s35, 1
	s_or_b32 s30, s34, s30
	s_lshl_b32 s59, s62, 8
	v_ashrrev_i32_e32 v42, 3, v227
	s_lshl_b32 s35, s30, 8
	s_waitcnt vmcnt(3)
	v_add_u32_e32 v10, s59, v42
	s_waitcnt vmcnt(0)
	v_add_u32_e32 v4, s35, v42
	v_lshlrev_b32_e32 v2, 4, v227
	v_min_i32_e32 v8, 0x107f, v10
	v_ashrrev_i32_e32 v5, 31, v4
	v_and_b32_e32 v2, 0x70, v2
	v_ashrrev_i32_e32 v9, 31, v8
	v_lshlrev_b64 v[4:5], 11, v[4:5]
	s_waitcnt lgkmcnt(0)
	v_lshl_add_u64 v[6:7], s[18:19], 0, v[2:3]
	v_lshlrev_b64 v[8:9], 11, v[8:9]
	v_lshl_add_u64 v[228:229], v[6:7], 0, v[8:9]
	v_min_i32_e32 v8, 0x103f, v10
	v_lshl_add_u64 v[4:5], s[16:17], 0, v[4:5]
	v_ashrrev_i32_e32 v9, 31, v8
	v_lshl_add_u64 v[230:231], v[4:5], 0, v[2:3]
	v_lshlrev_b64 v[8:9], 11, v[8:9]
	v_add_co_u32_e32 v232, vcc, s42, v230
	v_lshl_add_u64 v[36:37], v[6:7], 0, v[8:9]
	v_min_i32_e32 v8, 0xfff, v10
	v_addc_co_u32_e32 v233, vcc, 0, v231, vcc
	v_ashrrev_i32_e32 v9, 31, v8
	v_add_co_u32_e32 v16, vcc, s42, v36
	v_lshlrev_b64 v[8:9], 11, v[8:9]
	s_nop 0
	v_addc_co_u32_e32 v17, vcc, 0, v37, vcc
	v_lshl_add_u64 v[38:39], v[6:7], 0, v[8:9]
	v_min_i32_e32 v8, 0xfbf, v10
	v_add_co_u32_e32 v68, vcc, s43, v230
	v_ashrrev_i32_e32 v9, 31, v8
	s_nop 0
	v_addc_co_u32_e32 v69, vcc, 0, v231, vcc
	v_lshlrev_b64 v[8:9], 11, v[8:9]
	v_add_co_u32_e32 v24, vcc, s43, v38
	v_lshl_add_u64 v[40:41], v[6:7], 0, v[8:9]
	global_load_dwordx4 v[4:7], v[230:231], off
	global_load_dwordx4 v[8:11], v[228:229], off
	v_addc_co_u32_e32 v25, vcc, 0, v39, vcc
	global_load_dwordx4 v[16:19], v[16:17], off
	v_add_co_u32_e32 v28, vcc, s44, v40
	global_load_dwordx4 v[24:27], v[24:25], off
	s_nop 0
	v_addc_co_u32_e32 v29, vcc, 0, v41, vcc
	global_load_dwordx4 v[28:31], v[28:29], off
	v_add_co_u32_e32 v70, vcc, s44, v230
	global_load_dwordx4 v[12:15], v[232:233], off
	global_load_dwordx4 v[20:23], v[68:69], off
	v_addc_co_u32_e32 v71, vcc, 0, v231, vcc
	global_load_dwordx4 v[32:35], v[70:71], off
	v_mul_lo_u32 v42, v42, s46
	v_add3_u32 v251, s45, v2, v42
	v_add3_u32 v250, 0, v2, v42
	v_lshl_add_u64 v[238:239], v[36:37], 0, s[24:25]
	v_lshl_add_u64 v[234:235], v[38:39], 0, s[26:27]
	v_lshl_add_u64 v[236:237], v[40:41], 0, s[28:29]
	global_load_dwordx4 v[36:39], v[228:229], off offset:128
	global_load_dwordx4 v[40:43], v[238:239], off offset:128
	global_load_dwordx4 v[44:47], v[234:235], off offset:128
	global_load_dwordx4 v[48:51], v[236:237], off offset:128
	global_load_dwordx4 v[52:55], v[230:231], off offset:128
	global_load_dwordx4 v[56:59], v[232:233], off offset:128
	global_load_dwordx4 v[60:63], v[68:69], off offset:128
	global_load_dwordx4 v[64:67], v[70:71], off offset:128
	s_ashr_i32 s36, s60, 6
	s_bfe_u32 s37, s36, 0x10001
	s_ashr_i32 s38, s60, 8
	s_and_b64 s[30:31], s[6:7], exec
	s_cselect_b32 s37, s37, s38
	s_xor_b64 s[6:7], s[6:7], -1
	s_cmp_lt_i32 s36, 4
	v_and_b32_e32 v225, 31, v227
	s_cselect_b64 s[30:31], -1, 0
	s_lshl_b32 s36, s37, 7
	v_bfe_u32 v247, v227, 5, 1
	v_or_b32_e32 v2, s36, v225
	v_mul_lo_u32 v2, v2, s46
	v_lshlrev_b32_e32 v226, 4, v247
	s_lshl_b32 s61, s20, 6
	v_add3_u32 v248, 0, v2, v226
	v_or_b32_e32 v2, s61, v225
	v_mul_lo_u32 v2, v2, s46
	s_or_b64 s[30:31], s[6:7], s[30:31]
	v_add3_u32 v249, s45, v2, v226
	s_waitcnt vmcnt(14)
	ds_write_b128 v251, v[8:11]
	s_waitcnt vmcnt(13)
	ds_write_b128 v251, v[16:19] offset:9216
	s_waitcnt vmcnt(12)
	ds_write_b128 v251, v[24:27] offset:18432
	s_waitcnt vmcnt(11)
	ds_write_b128 v251, v[28:31] offset:27648
	ds_write_b128 v250, v[4:7]
	s_waitcnt vmcnt(10)
	ds_write_b128 v250, v[12:15] offset:9216
	s_waitcnt vmcnt(9)
	ds_write_b128 v250, v[20:23] offset:18432
	s_waitcnt vmcnt(8)
	ds_write_b128 v250, v[32:35] offset:27648
	s_waitcnt lgkmcnt(0)
	s_barrier
	s_andn2_b64 vcc, exec, s[30:31]
	s_cbranch_vccnz .Lp1_stage_only
	s_lshr_b32 s6, s60, 6
	s_cmp_ge_u32 s6, 4
	s_cbranch_scc0 .Lp1_prio_skip
	s_setprio 1
.Lp1_prio_skip:
	v_lshrrev_b32_e32 v227, 3, v223
	v_lshlrev_b32_e32 v227, 11, v227
	v_lshlrev_b32_e32 v2, 4, v223
	v_and_b32_e32 v2, 0x70, v2
	v_or_b32_e32 v227, v227, v2
	s_lshl_b32 s6, s35, 11
	s_add_u32 s74, s16, s6
	s_addc_u32 s75, s17, 0
	s_add_u32 s76, s74, 0x20000
	s_addc_u32 s77, s75, 0
	s_add_u32 s78, s74, 0x40000
	s_addc_u32 s79, s75, 0
	s_add_u32 s80, s74, 0x60000
	s_addc_u32 s81, s75, 0
	s_lshl_b32 s6, s59, 11
	s_add_u32 s82, s18, s6
	s_addc_u32 s83, s19, 0
	s_add_u32 s84, s82, 0x20000
	s_addc_u32 s85, s83, 0
	s_add_u32 s86, s82, 0x40000
	s_addc_u32 s87, s83, 0
	s_add_u32 s92, s82, 0x60000
	s_addc_u32 s93, s83, 0
	global_load_dwordx4 v[146:149], v227, s[74:75] offset:256
	global_load_dwordx4 v[178:181], v227, s[82:83] offset:256
	global_load_dwordx4 v[150:153], v227, s[76:77] offset:256
	global_load_dwordx4 v[182:185], v227, s[84:85] offset:256
	global_load_dwordx4 v[154:157], v227, s[78:79] offset:256
	global_load_dwordx4 v[186:189], v227, s[86:87] offset:256
	global_load_dwordx4 v[158:161], v227, s[80:81] offset:256
	global_load_dwordx4 v[190:193], v227, s[92:93] offset:256
	global_load_dwordx4 v[162:165], v227, s[74:75] offset:384
	global_load_dwordx4 v[194:197], v227, s[82:83] offset:384
	global_load_dwordx4 v[166:169], v227, s[76:77] offset:384
	global_load_dwordx4 v[198:201], v227, s[84:85] offset:384
	global_load_dwordx4 v[170:173], v227, s[78:79] offset:384
	global_load_dwordx4 v[202:205], v227, s[86:87] offset:384
	global_load_dwordx4 v[174:177], v227, s[80:81] offset:384
	global_load_dwordx4 v[206:209], v227, s[92:93] offset:384
	s_waitcnt vmcnt(23)
	ds_write_b128 v251, v[36:39] offset:36864
	s_waitcnt vmcnt(22)
	ds_write_b128 v251, v[40:43] offset:46080
	s_waitcnt vmcnt(21)
;     ...
;   for (int i = 0; i < 4; ++i) { ra[i] = *(const u32x4*)(Ag + (size_t)(64 * i) * K); rb[i] = *(const u32x4*)(Bg[i]); }
; #pragma unroll
;   for (int i = 0; i < 4; ++i) { *(u32x4*)(As0 + (srow + 64 * i) * LD + skc * 8) = ra[i]; *(u32x4*)(Bs0 + (srow + 64 * i) * LD + skc * 8) = rb[i]; }
;   if (nk > 1) {
; #pragma unroll
;     for (int i = 0; i < 4; ++i) { ra[i] = *(const u32x4*)(Ag + (size_t)(64 * i) * K + 64); rb[i] = *(const u32x4*)(Bg[i] + 64); }
;   }
;   for (int kt = 0; kt < nk; ++kt) {
;     __syncthreads();
;     if (kt + 1 < nk) {
;       u16* aw = As0 + ((kt + 1) & 1) * 256 * LD;
;       u16* bw = Bs0 + ((kt + 1) & 1) * 256 * LD;
; #pragma unroll
;       for (int i = 0; i < 4; ++i) { *(u32x4*)(aw + (srow + 64 * i) * LD + skc * 8) = ra[i]; *(u32x4*)(bw + (srow + 64 * i) * LD + skc * 8) = rb[i]; }
;     }
;     if (kt + 2 < nk) {
; #pragma unroll
;       for (int i = 0; i < 4; ++i) { ra[i] = *(const u32x4*)(Ag + (size_t)(64 * i) * K + (kt + 2) * 64); rb[i] = *(const u32x4*)(Bg[i] + (kt + 2) * 64); }
;     }
;     __builtin_amdgcn_sched_barrier(0);
;     const u16* as = As0 + (kt & 1) * 256 * LD + (wr * 128 + l31) * LD + h * 8;
;     const u16* bs = Bs0 + (kt & 1) * 256 * LD + (wc * 64 + l31) * LD + h * 8;
;     if (domma)
; #pragma unroll
;     for (int ks = 0; ks < 4; ++ks) {
;       bf16x8 wf[2], xf[4];
; #pragma unroll
;       for (int ct = 0; ct < 2; ++ct) wf[ct] = *(const bf16x8*)(bs + ct * 32 * LD + ks * 16);
; #pragma unroll
;       for (int tt = 0; tt < 4; ++tt) xf[tt] = *(const bf16x8*)(as + tt * 32 * LD + ks * 16);
; #pragma unroll
;       for (int ct = 0; ct < 2; ++ct)
; #pragma unroll
;         for (int tt = 0; tt < 4; ++tt) acc[ct][tt] = __builtin_amdgcn_mfma_f32_32x32x16_bf16(wf[ct], xf[tt], acc[ct][tt], 0, 0, 0);
;     }
;     __builtin_amdgcn_sched_barrier(0);
	ds_write_b128 v251, v[44:47] offset:55296
	s_waitcnt vmcnt(20)
	ds_write_b128 v251, v[48:51] offset:64512
	s_waitcnt vmcnt(19)
	ds_write_b128 v250, v[52:55] offset:36864
	s_waitcnt vmcnt(18)
	ds_write_b128 v250, v[56:59] offset:46080
	s_waitcnt vmcnt(17)
	ds_write_b128 v250, v[60:63] offset:55296
	s_waitcnt vmcnt(16)
	ds_write_b128 v250, v[64:67] offset:64512
	ds_read_b128 v[210:213], v249
	ds_read_b128 v[236:239], v248
	ds_read_b128 v[214:217], v249 offset:4608
	ds_read_b128 v[2:5], v248 offset:4608
	ds_read_b128 v[6:9], v248 offset:9216
	ds_read_b128 v[10:13], v248 offset:13824
	s_waitcnt lgkmcnt(4)
	v_mfma_f32_32x32x16_bf16 v[114:129], v[210:213], v[236:239], 0
	ds_read_b128 v[228:231], v249 offset:32
	s_waitcnt lgkmcnt(4)
	v_mfma_f32_32x32x16_bf16 v[130:145], v[214:217], v[236:239], 0
	ds_read_b128 v[14:17], v248 offset:32
	s_waitcnt lgkmcnt(4)
	v_mfma_f32_32x32x16_bf16 v[82:97], v[210:213], v[2:5], 0
	ds_read_b128 v[232:235], v249 offset:4640
	v_mfma_f32_32x32x16_bf16 v[98:113], v[214:217], v[2:5], 0
	ds_read_b128 v[236:239], v248 offset:4640
	s_waitcnt lgkmcnt(5)
	v_mfma_f32_32x32x16_bf16 v[50:65], v[210:213], v[6:9], 0
	ds_read_b128 v[2:5], v248 offset:9248
	v_mfma_f32_32x32x16_bf16 v[66:81], v[214:217], v[6:9], 0
	s_waitcnt lgkmcnt(5)
	v_mfma_f32_32x32x16_bf16 v[18:33], v[210:213], v[10:13], 0
	ds_read_b128 v[6:9], v248 offset:13856
	v_mfma_f32_32x32x16_bf16 v[34:49], v[214:217], v[10:13], 0
	s_waitcnt lgkmcnt(4)
	v_mfma_f32_32x32x16_bf16 v[114:129], v[228:231], v[14:17], v[114:129]
	ds_read_b128 v[210:213], v249 offset:64
	s_waitcnt lgkmcnt(4)
	v_mfma_f32_32x32x16_bf16 v[130:145], v[232:235], v[14:17], v[130:145]
	ds_read_b128 v[10:13], v248 offset:64
	s_waitcnt lgkmcnt(4)
	v_mfma_f32_32x32x16_bf16 v[82:97], v[228:231], v[236:239], v[82:97]
	ds_read_b128 v[214:217], v249 offset:4672
	v_mfma_f32_32x32x16_bf16 v[98:113], v[232:235], v[236:239], v[98:113]
	ds_read_b128 v[14:17], v248 offset:4672
	s_waitcnt lgkmcnt(5)
	v_mfma_f32_32x32x16_bf16 v[50:65], v[228:231], v[2:5], v[50:65]
	ds_read_b128 v[236:239], v248 offset:9280
	v_mfma_f32_32x32x16_bf16 v[66:81], v[232:235], v[2:5], v[66:81]
	s_waitcnt lgkmcnt(5)
	v_mfma_f32_32x32x16_bf16 v[18:33], v[228:231], v[6:9], v[18:33]
	ds_read_b128 v[2:5], v248 offset:13888
	v_mfma_f32_32x32x16_bf16 v[34:49], v[232:235], v[6:9], v[34:49]
	s_waitcnt lgkmcnt(4)
	v_mfma_f32_32x32x16_bf16 v[114:129], v[210:213], v[10:13], v[114:129]
	ds_read_b128 v[228:231], v249 offset:96
	s_waitcnt lgkmcnt(4)
	v_mfma_f32_32x32x16_bf16 v[130:145], v[214:217], v[10:13], v[130:145]
	ds_read_b128 v[6:9], v248 offset:96
	s_waitcnt lgkmcnt(4)
	v_mfma_f32_32x32x16_bf16 v[82:97], v[210:213], v[14:17], v[82:97]
	ds_read_b128 v[232:235], v249 offset:4704
	v_mfma_f32_32x32x16_bf16 v[98:113], v[214:217], v[14:17], v[98:113]
	ds_read_b128 v[10:13], v248 offset:4704
	s_waitcnt lgkmcnt(5)
	v_mfma_f32_32x32x16_bf16 v[50:65], v[210:213], v[236:239], v[50:65]
	ds_read_b128 v[14:17], v248 offset:9312
	v_mfma_f32_32x32x16_bf16 v[66:81], v[214:217], v[236:239], v[66:81]
	s_waitcnt lgkmcnt(5)
	v_mfma_f32_32x32x16_bf16 v[18:33], v[210:213], v[2:5], v[18:33]
	ds_read_b128 v[236:239], v248 offset:13920
	v_mfma_f32_32x32x16_bf16 v[34:49], v[214:217], v[2:5], v[34:49]
	s_waitcnt lgkmcnt(4)
	v_mfma_f32_32x32x16_bf16 v[114:129], v[228:231], v[6:9], v[114:129]
	s_waitcnt lgkmcnt(3)
	v_mfma_f32_32x32x16_bf16 v[130:145], v[232:235], v[6:9], v[130:145]
	s_waitcnt lgkmcnt(2)
	v_mfma_f32_32x32x16_bf16 v[82:97], v[228:231], v[10:13], v[82:97]
	v_mfma_f32_32x32x16_bf16 v[98:113], v[232:235], v[10:13], v[98:113]
	s_waitcnt lgkmcnt(1)
	v_mfma_f32_32x32x16_bf16 v[50:65], v[228:231], v[14:17], v[50:65]
	v_mfma_f32_32x32x16_bf16 v[66:81], v[232:235], v[14:17], v[66:81]
	s_waitcnt lgkmcnt(0)
	v_mfma_f32_32x32x16_bf16 v[18:33], v[228:231], v[236:239], v[18:33]
	v_mfma_f32_32x32x16_bf16 v[34:49], v[232:235], v[236:239], v[34:49]
	s_barrier
	ds_read_b128 v[210:213], v249 offset:36864
	ds_read_b128 v[236:239], v248 offset:36864
	ds_read_b128 v[214:217], v249 offset:41472
	ds_read_b128 v[2:5], v248 offset:41472
	ds_read_b128 v[6:9], v248 offset:46080
	ds_read_b128 v[10:13], v248 offset:50688
	s_waitcnt lgkmcnt(4)
	v_mfma_f32_32x32x16_bf16 v[114:129], v[210:213], v[236:239], v[114:129]
	ds_read_b128 v[228:231], v249 offset:36896
	s_waitcnt lgkmcnt(4)
	v_mfma_f32_32x32x16_bf16 v[130:145], v[214:217], v[236:239], v[130:145]
	ds_read_b128 v[14:17], v248 offset:36896
	s_waitcnt lgkmcnt(4)
	v_mfma_f32_32x32x16_bf16 v[82:97], v[210:213], v[2:5], v[82:97]
	ds_read_b128 v[232:235], v249 offset:41504
	v_mfma_f32_32x32x16_bf16 v[98:113], v[214:217], v[2:5], v[98:113]
	ds_read_b128 v[236:239], v248 offset:41504
	s_waitcnt vmcnt(15)
	ds_write_b128 v250, v[146:149]
	s_waitcnt lgkmcnt(6)
	v_mfma_f32_32x32x16_bf16 v[50:65], v[210:213], v[6:9], v[50:65]
	ds_read_b128 v[2:5], v248 offset:46112
	v_mfma_f32_32x32x16_bf16 v[66:81], v[214:217], v[6:9], v[66:81]
	global_load_dwordx4 v[146:149], v227, s[74:75] offset:512
	s_waitcnt lgkmcnt(6)
	v_mfma_f32_32x32x16_bf16 v[18:33], v[210:213], v[10:13], v[18:33]
	ds_read_b128 v[6:9], v248 offset:50720
	s_waitcnt vmcnt(15)
	ds_write_b128 v251, v[178:181]
	v_mfma_f32_32x32x16_bf16 v[34:49], v[214:217], v[10:13], v[34:49]
	s_waitcnt lgkmcnt(6)
	v_mfma_f32_32x32x16_bf16 v[114:129], v[228:231], v[14:17], v[114:129]
	ds_read_b128 v[210:213], v249 offset:36928
	global_load_dwordx4 v[178:181], v227, s[82:83] offset:512
	s_waitcnt lgkmcnt(6)
	v_mfma_f32_32x32x16_bf16 v[130:145], v[232:235], v[14:17], v[130:145]
	ds_read_b128 v[10:13], v248 offset:36928
	s_waitcnt vmcnt(15)
	ds_write_b128 v250, v[150:153] offset:9216
	s_waitcnt lgkmcnt(7)
;     ...
;   for (int kt = 0; kt < nk; ++kt) {
;     __syncthreads();
;     if (kt + 1 < nk) {
;       u16* aw = As0 + ((kt + 1) & 1) * 256 * LD;
;       u16* bw = Bs0 + ((kt + 1) & 1) * 256 * LD;
; #pragma unroll
;       for (int i = 0; i < 4; ++i) { *(u32x4*)(aw + (srow + 64 * i) * LD + skc * 8) = ra[i]; *(u32x4*)(bw + (srow + 64 * i) * LD + skc * 8) = rb[i]; }
;     }
;     if (kt + 2 < nk) {
; #pragma unroll
;       for (int i = 0; i < 4; ++i) { ra[i] = *(const u32x4*)(Ag + (size_t)(64 * i) * K + (kt + 2) * 64); rb[i] = *(const u32x4*)(Bg[i] + (kt + 2) * 64); }
;     }
;     __builtin_amdgcn_sched_barrier(0);
;     const u16* as = As0 + (kt & 1) * 256 * LD + (wr * 128 + l31) * LD + h * 8;
;     const u16* bs = Bs0 + (kt & 1) * 256 * LD + (wc * 64 + l31) * LD + h * 8;
;     if (domma)
; #pragma unroll
;     for (int ks = 0; ks < 4; ++ks) {
;       bf16x8 wf[2], xf[4];
; #pragma unroll
;       for (int ct = 0; ct < 2; ++ct) wf[ct] = *(const bf16x8*)(bs + ct * 32 * LD + ks * 16);
; #pragma unroll
;       for (int tt = 0; tt < 4; ++tt) xf[tt] = *(const bf16x8*)(as + tt * 32 * LD + ks * 16);
; #pragma unroll
;       for (int ct = 0; ct < 2; ++ct)
; #pragma unroll
;         for (int tt = 0; tt < 4; ++tt) acc[ct][tt] = __builtin_amdgcn_mfma_f32_32x32x16_bf16(wf[ct], xf[tt], acc[ct][tt], 0, 0, 0);
;     }
;     __builtin_amdgcn_sched_barrier(0);
	v_mfma_f32_32x32x16_bf16 v[82:97], v[228:231], v[236:239], v[82:97]
	ds_read_b128 v[214:217], v249 offset:41536
	v_mfma_f32_32x32x16_bf16 v[98:113], v[232:235], v[236:239], v[98:113]
	ds_read_b128 v[14:17], v248 offset:41536
	global_load_dwordx4 v[150:153], v227, s[76:77] offset:512
	s_waitcnt lgkmcnt(7)
	v_mfma_f32_32x32x16_bf16 v[50:65], v[228:231], v[2:5], v[50:65]
	ds_read_b128 v[236:239], v248 offset:46144
	s_waitcnt vmcnt(15)
	ds_write_b128 v251, v[182:185] offset:9216
	v_mfma_f32_32x32x16_bf16 v[66:81], v[232:235], v[2:5], v[66:81]
	s_waitcnt lgkmcnt(8)
	v_mfma_f32_32x32x16_bf16 v[18:33], v[228:231], v[6:9], v[18:33]
	ds_read_b128 v[2:5], v248 offset:50752
	global_load_dwordx4 v[182:185], v227, s[84:85] offset:512
	v_mfma_f32_32x32x16_bf16 v[34:49], v[232:235], v[6:9], v[34:49]
	s_waitcnt vmcnt(15)
	ds_write_b128 v250, v[154:157] offset:18432
	s_waitcnt lgkmcnt(7)
	v_mfma_f32_32x32x16_bf16 v[114:129], v[210:213], v[10:13], v[114:129]
	ds_read_b128 v[228:231], v249 offset:36960
	s_waitcnt lgkmcnt(6)
	v_mfma_f32_32x32x16_bf16 v[130:145], v[214:217], v[10:13], v[130:145]
	ds_read_b128 v[6:9], v248 offset:36960
	global_load_dwordx4 v[154:157], v227, s[78:79] offset:512
	s_waitcnt lgkmcnt(6)
	v_mfma_f32_32x32x16_bf16 v[82:97], v[210:213], v[14:17], v[82:97]
	ds_read_b128 v[232:235], v249 offset:41568
	s_waitcnt vmcnt(15)
	ds_write_b128 v251, v[186:189] offset:18432
	v_mfma_f32_32x32x16_bf16 v[98:113], v[214:217], v[14:17], v[98:113]
	ds_read_b128 v[10:13], v248 offset:41568
	s_waitcnt lgkmcnt(8)
	v_mfma_f32_32x32x16_bf16 v[50:65], v[210:213], v[236:239], v[50:65]
	ds_read_b128 v[14:17], v248 offset:46176
	global_load_dwordx4 v[186:189], v227, s[86:87] offset:512
	v_mfma_f32_32x32x16_bf16 v[66:81], v[214:217], v[236:239], v[66:81]
	s_waitcnt vmcnt(15)
	ds_write_b128 v250, v[158:161] offset:27648
	s_waitcnt lgkmcnt(8)
	v_mfma_f32_32x32x16_bf16 v[18:33], v[210:213], v[2:5], v[18:33]
	ds_read_b128 v[236:239], v248 offset:50784
	v_mfma_f32_32x32x16_bf16 v[34:49], v[214:217], v[2:5], v[34:49]
	global_load_dwordx4 v[158:161], v227, s[80:81] offset:512
	s_waitcnt lgkmcnt(6)
	v_mfma_f32_32x32x16_bf16 v[114:129], v[228:231], v[6:9], v[114:129]
	s_waitcnt vmcnt(15)
	ds_write_b128 v251, v[190:193] offset:27648
	s_waitcnt lgkmcnt(6)
	v_mfma_f32_32x32x16_bf16 v[130:145], v[232:235], v[6:9], v[130:145]
	s_waitcnt lgkmcnt(4)
	v_mfma_f32_32x32x16_bf16 v[82:97], v[228:231], v[10:13], v[82:97]
	global_load_dwordx4 v[190:193], v227, s[92:93] offset:512
	v_mfma_f32_32x32x16_bf16 v[98:113], v[232:235], v[10:13], v[98:113]
	s_waitcnt lgkmcnt(3)
	v_mfma_f32_32x32x16_bf16 v[50:65], v[228:231], v[14:17], v[50:65]
	v_mfma_f32_32x32x16_bf16 v[66:81], v[232:235], v[14:17], v[66:81]
	s_waitcnt lgkmcnt(1)
	v_mfma_f32_32x32x16_bf16 v[18:33], v[228:231], v[236:239], v[18:33]
	v_mfma_f32_32x32x16_bf16 v[34:49], v[232:235], v[236:239], v[34:49]
	s_waitcnt lgkmcnt(0)
	s_barrier
	ds_read_b128 v[210:213], v249
	ds_read_b128 v[236:239], v248
	ds_read_b128 v[214:217], v249 offset:4608
	ds_read_b128 v[2:5], v248 offset:4608
	ds_read_b128 v[6:9], v248 offset:9216
	ds_read_b128 v[10:13], v248 offset:13824
	s_waitcnt lgkmcnt(4)
	v_mfma_f32_32x32x16_bf16 v[114:129], v[210:213], v[236:239], v[114:129]
	ds_read_b128 v[228:231], v249 offset:32
	s_waitcnt lgkmcnt(4)
	v_mfma_f32_32x32x16_bf16 v[130:145], v[214:217], v[236:239], v[130:145]
	ds_read_b128 v[14:17], v248 offset:32
	s_waitcnt lgkmcnt(4)
	v_mfma_f32_32x32x16_bf16 v[82:97], v[210:213], v[2:5], v[82:97]
	ds_read_b128 v[232:235], v249 offset:4640
	v_mfma_f32_32x32x16_bf16 v[98:113], v[214:217], v[2:5], v[98:113]
	ds_read_b128 v[236:239], v248 offset:4640
	s_waitcnt vmcnt(15)
	ds_write_b128 v250, v[162:165] offset:36864
	s_waitcnt lgkmcnt(6)
	v_mfma_f32_32x32x16_bf16 v[50:65], v[210:213], v[6:9], v[50:65]
	ds_read_b128 v[2:5], v248 offset:9248
	v_mfma_f32_32x32x16_bf16 v[66:81], v[214:217], v[6:9], v[66:81]
	global_load_dwordx4 v[162:165], v227, s[74:75] offset:640
	s_waitcnt lgkmcnt(6)
	v_mfma_f32_32x32x16_bf16 v[18:33], v[210:213], v[10:13], v[18:33]
	ds_read_b128 v[6:9], v248 offset:13856
	s_waitcnt vmcnt(15)
	ds_write_b128 v251, v[194:197] offset:36864
	v_mfma_f32_32x32x16_bf16 v[34:49], v[214:217], v[10:13], v[34:49]
	s_waitcnt lgkmcnt(6)
	v_mfma_f32_32x32x16_bf16 v[114:129], v[228:231], v[14:17], v[114:129]
	ds_read_b128 v[210:213], v249 offset:64
	global_load_dwordx4 v[194:197], v227, s[82:83] offset:640
	s_waitcnt lgkmcnt(6)
	v_mfma_f32_32x32x16_bf16 v[130:145], v[232:235], v[14:17], v[130:145]
	ds_read_b128 v[10:13], v248 offset:64
	s_waitcnt vmcnt(15)
	ds_write_b128 v250, v[166:169] offset:46080
	s_waitcnt lgkmcnt(7)
	v_mfma_f32_32x32x16_bf16 v[82:97], v[228:231], v[236:239], v[82:97]
	ds_read_b128 v[214:217], v249 offset:4672
	v_mfma_f32_32x32x16_bf16 v[98:113], v[232:235], v[236:239], v[98:113]
	ds_read_b128 v[14:17], v248 offset:4672
	global_load_dwordx4 v[166:169], v227, s[76:77] offset:640
	s_waitcnt lgkmcnt(7)
	v_mfma_f32_32x32x16_bf16 v[50:65], v[228:231], v[2:5], v[50:65]
	ds_read_b128 v[236:239], v248 offset:9280
	s_waitcnt vmcnt(15)
	ds_write_b128 v251, v[198:201] offset:46080
	v_mfma_f32_32x32x16_bf16 v[66:81], v[232:235], v[2:5], v[66:81]
	s_waitcnt lgkmcnt(8)
	v_mfma_f32_32x32x16_bf16 v[18:33], v[228:231], v[6:9], v[18:33]
	ds_read_b128 v[2:5], v248 offset:13888
	global_load_dwordx4 v[198:201], v227, s[84:85] offset:640
	v_mfma_f32_32x32x16_bf16 v[34:49], v[232:235], v[6:9], v[34:49]
	s_waitcnt vmcnt(15)
	ds_write_b128 v250, v[170:173] offset:55296
	s_waitcnt lgkmcnt(7)
	v_mfma_f32_32x32x16_bf16 v[114:129], v[210:213], v[10:13], v[114:129]
	ds_read_b128 v[228:231], v249 offset:96
	s_waitcnt lgkmcnt(6)
;     ...
;   for (int kt = 0; kt < nk; ++kt) {
;     __syncthreads();
;     if (kt + 1 < nk) {
;       u16* aw = As0 + ((kt + 1) & 1) * 256 * LD;
;       u16* bw = Bs0 + ((kt + 1) & 1) * 256 * LD;
; #pragma unroll
;       for (int i = 0; i < 4; ++i) { *(u32x4*)(aw + (srow + 64 * i) * LD + skc * 8) = ra[i]; *(u32x4*)(bw + (srow + 64 * i) * LD + skc * 8) = rb[i]; }
;     }
;     if (kt + 2 < nk) {
; #pragma unroll
;       for (int i = 0; i < 4; ++i) { ra[i] = *(const u32x4*)(Ag + (size_t)(64 * i) * K + (kt + 2) * 64); rb[i] = *(const u32x4*)(Bg[i] + (kt + 2) * 64); }
;     }
;     __builtin_amdgcn_sched_barrier(0);
;     const u16* as = As0 + (kt & 1) * 256 * LD + (wr * 128 + l31) * LD + h * 8;
;     const u16* bs = Bs0 + (kt & 1) * 256 * LD + (wc * 64 + l31) * LD + h * 8;
;     if (domma)
; #pragma unroll
;     for (int ks = 0; ks < 4; ++ks) {
;       bf16x8 wf[2], xf[4];
; #pragma unroll
;       for (int ct = 0; ct < 2; ++ct) wf[ct] = *(const bf16x8*)(bs + ct * 32 * LD + ks * 16);
; #pragma unroll
;       for (int tt = 0; tt < 4; ++tt) xf[tt] = *(const bf16x8*)(as + tt * 32 * LD + ks * 16);
; #pragma unroll
;       for (int ct = 0; ct < 2; ++ct)
; #pragma unroll
;         for (int tt = 0; tt < 4; ++tt) acc[ct][tt] = __builtin_amdgcn_mfma_f32_32x32x16_bf16(wf[ct], xf[tt], acc[ct][tt], 0, 0, 0);
;     }
;     __builtin_amdgcn_sched_barrier(0);
	v_mfma_f32_32x32x16_bf16 v[130:145], v[214:217], v[10:13], v[130:145]
	ds_read_b128 v[6:9], v248 offset:96
	global_load_dwordx4 v[170:173], v227, s[78:79] offset:640
	s_waitcnt lgkmcnt(6)
	v_mfma_f32_32x32x16_bf16 v[82:97], v[210:213], v[14:17], v[82:97]
	ds_read_b128 v[232:235], v249 offset:4704
	s_waitcnt vmcnt(15)
	ds_write_b128 v251, v[202:205] offset:55296
	v_mfma_f32_32x32x16_bf16 v[98:113], v[214:217], v[14:17], v[98:113]
	ds_read_b128 v[10:13], v248 offset:4704
	s_waitcnt lgkmcnt(8)
	v_mfma_f32_32x32x16_bf16 v[50:65], v[210:213], v[236:239], v[50:65]
	ds_read_b128 v[14:17], v248 offset:9312
	global_load_dwordx4 v[202:205], v227, s[86:87] offset:640
	v_mfma_f32_32x32x16_bf16 v[66:81], v[214:217], v[236:239], v[66:81]
	s_waitcnt vmcnt(15)
	ds_write_b128 v250, v[174:177] offset:64512
	s_waitcnt lgkmcnt(8)
	v_mfma_f32_32x32x16_bf16 v[18:33], v[210:213], v[2:5], v[18:33]
	ds_read_b128 v[236:239], v248 offset:13920
	v_mfma_f32_32x32x16_bf16 v[34:49], v[214:217], v[2:5], v[34:49]
	global_load_dwordx4 v[174:177], v227, s[80:81] offset:640
	s_waitcnt lgkmcnt(6)
	v_mfma_f32_32x32x16_bf16 v[114:129], v[228:231], v[6:9], v[114:129]
	s_waitcnt vmcnt(15)
	ds_write_b128 v251, v[206:209] offset:64512
	s_waitcnt lgkmcnt(6)
	v_mfma_f32_32x32x16_bf16 v[130:145], v[232:235], v[6:9], v[130:145]
	s_waitcnt lgkmcnt(4)
	v_mfma_f32_32x32x16_bf16 v[82:97], v[228:231], v[10:13], v[82:97]
	global_load_dwordx4 v[206:209], v227, s[92:93] offset:640
	v_mfma_f32_32x32x16_bf16 v[98:113], v[232:235], v[10:13], v[98:113]
	s_waitcnt lgkmcnt(3)
	v_mfma_f32_32x32x16_bf16 v[50:65], v[228:231], v[14:17], v[50:65]
	v_mfma_f32_32x32x16_bf16 v[66:81], v[232:235], v[14:17], v[66:81]
	s_waitcnt lgkmcnt(1)
	v_mfma_f32_32x32x16_bf16 v[18:33], v[228:231], v[236:239], v[18:33]
	v_mfma_f32_32x32x16_bf16 v[34:49], v[232:235], v[236:239], v[34:49]
	s_waitcnt lgkmcnt(0)
	s_barrier
	ds_read_b128 v[210:213], v249 offset:36864
	ds_read_b128 v[236:239], v248 offset:36864
	ds_read_b128 v[214:217], v249 offset:41472
	ds_read_b128 v[2:5], v248 offset:41472
	ds_read_b128 v[6:9], v248 offset:46080
	ds_read_b128 v[10:13], v248 offset:50688
	s_waitcnt lgkmcnt(4)
	v_mfma_f32_32x32x16_bf16 v[114:129], v[210:213], v[236:239], v[114:129]
	ds_read_b128 v[228:231], v249 offset:36896
	s_waitcnt lgkmcnt(4)
	v_mfma_f32_32x32x16_bf16 v[130:145], v[214:217], v[236:239], v[130:145]
	ds_read_b128 v[14:17], v248 offset:36896
	s_waitcnt lgkmcnt(4)
	v_mfma_f32_32x32x16_bf16 v[82:97], v[210:213], v[2:5], v[82:97]
	ds_read_b128 v[232:235], v249 offset:41504
	v_mfma_f32_32x32x16_bf16 v[98:113], v[214:217], v[2:5], v[98:113]
	ds_read_b128 v[236:239], v248 offset:41504
	s_waitcnt vmcnt(15)
	ds_write_b128 v250, v[146:149]
	s_waitcnt lgkmcnt(6)
	v_mfma_f32_32x32x16_bf16 v[50:65], v[210:213], v[6:9], v[50:65]
	ds_read_b128 v[2:5], v248 offset:46112
	v_mfma_f32_32x32x16_bf16 v[66:81], v[214:217], v[6:9], v[66:81]
	global_load_dwordx4 v[146:149], v227, s[74:75] offset:768
	s_waitcnt lgkmcnt(6)
	v_mfma_f32_32x32x16_bf16 v[18:33], v[210:213], v[10:13], v[18:33]
	ds_read_b128 v[6:9], v248 offset:50720
	s_waitcnt vmcnt(15)
	ds_write_b128 v251, v[178:181]
	v_mfma_f32_32x32x16_bf16 v[34:49], v[214:217], v[10:13], v[34:49]
	s_waitcnt lgkmcnt(6)
	v_mfma_f32_32x32x16_bf16 v[114:129], v[228:231], v[14:17], v[114:129]
	ds_read_b128 v[210:213], v249 offset:36928
	global_load_dwordx4 v[178:181], v227, s[82:83] offset:768
	s_waitcnt lgkmcnt(6)
	v_mfma_f32_32x32x16_bf16 v[130:145], v[232:235], v[14:17], v[130:145]
	ds_read_b128 v[10:13], v248 offset:36928
	s_waitcnt vmcnt(15)
	ds_write_b128 v250, v[150:153] offset:9216
	s_waitcnt lgkmcnt(7)
	v_mfma_f32_32x32x16_bf16 v[82:97], v[228:231], v[236:239], v[82:97]
	ds_read_b128 v[214:217], v249 offset:41536
	v_mfma_f32_32x32x16_bf16 v[98:113], v[232:235], v[236:239], v[98:113]
	ds_read_b128 v[14:17], v248 offset:41536
	global_load_dwordx4 v[150:153], v227, s[76:77] offset:768
	s_waitcnt lgkmcnt(7)
	v_mfma_f32_32x32x16_bf16 v[50:65], v[228:231], v[2:5], v[50:65]
	ds_read_b128 v[236:239], v248 offset:46144
	s_waitcnt vmcnt(15)
	ds_write_b128 v251, v[182:185] offset:9216
	v_mfma_f32_32x32x16_bf16 v[66:81], v[232:235], v[2:5], v[66:81]
	s_waitcnt lgkmcnt(8)
	v_mfma_f32_32x32x16_bf16 v[18:33], v[228:231], v[6:9], v[18:33]
	ds_read_b128 v[2:5], v248 offset:50752
	global_load_dwordx4 v[182:185], v227, s[84:85] offset:768
	v_mfma_f32_32x32x16_bf16 v[34:49], v[232:235], v[6:9], v[34:49]
	s_waitcnt vmcnt(15)
	ds_write_b128 v250, v[154:157] offset:18432
	s_waitcnt lgkmcnt(7)
	v_mfma_f32_32x32x16_bf16 v[114:129], v[210:213], v[10:13], v[114:129]
	ds_read_b128 v[228:231], v249 offset:36960
	s_waitcnt lgkmcnt(6)
	v_mfma_f32_32x32x16_bf16 v[130:145], v[214:217], v[10:13], v[130:145]
	ds_read_b128 v[6:9], v248 offset:36960
	global_load_dwordx4 v[154:157], v227, s[78:79] offset:768
	s_waitcnt lgkmcnt(6)
	v_mfma_f32_32x32x16_bf16 v[82:97], v[210:213], v[14:17], v[82:97]
	ds_read_b128 v[232:235], v249 offset:41568
	s_waitcnt vmcnt(15)
	ds_write_b128 v251, v[186:189] offset:18432
	v_mfma_f32_32x32x16_bf16 v[98:113], v[214:217], v[14:17], v[98:113]
	ds_read_b128 v[10:13], v248 offset:41568
	s_waitcnt lgkmcnt(8)
	v_mfma_f32_32x32x16_bf16 v[50:65], v[210:213], v[236:239], v[50:65]
	ds_read_b128 v[14:17], v248 offset:46176
	global_load_dwordx4 v[186:189], v227, s[86:87] offset:768
	v_mfma_f32_32x32x16_bf16 v[66:81], v[214:217], v[236:239], v[66:81]
	s_waitcnt vmcnt(15)
	ds_write_b128 v250, v[158:161] offset:27648
	s_waitcnt lgkmcnt(8)
	v_mfma_f32_32x32x16_bf16 v[18:33], v[210:213], v[2:5], v[18:33]
	ds_read_b128 v[236:239], v248 offset:50784
	v_mfma_f32_32x32x16_bf16 v[34:49], v[214:217], v[2:5], v[34:49]
	global_load_dwordx4 v[158:161], v227, s[80:81] offset:768
	s_waitcnt lgkmcnt(6)
	v_mfma_f32_32x32x16_bf16 v[114:129], v[228:231], v[6:9], v[114:129]
	s_waitcnt vmcnt(15)
	ds_write_b128 v251, v[190:193] offset:27648
	s_waitcnt lgkmcnt(6)
	v_mfma_f32_32x32x16_bf16 v[130:145], v[232:235], v[6:9], v[130:145]
	s_waitcnt lgkmcnt(4)
	v_mfma_f32_32x32x16_bf16 v[82:97], v[228:231], v[10:13], v[82:97]
	global_load_dwordx4 v[190:193], v227, s[92:93] offset:768
	v_mfma_f32_32x32x16_bf16 v[98:113], v[232:235], v[10:13], v[98:113]
	s_waitcnt lgkmcnt(3)
	v_mfma_f32_32x32x16_bf16 v[50:65], v[228:231], v[14:17], v[50:65]
	v_mfma_f32_32x32x16_bf16 v[66:81], v[232:235], v[14:17], v[66:81]
	s_waitcnt lgkmcnt(1)
	v_mfma_f32_32x32x16_bf16 v[18:33], v[228:231], v[236:239], v[18:33]
	v_mfma_f32_32x32x16_bf16 v[34:49], v[232:235], v[236:239], v[34:49]
	s_waitcnt lgkmcnt(0)
	s_barrier
;     ...
;   for (int kt = 0; kt < nk; ++kt) {
;     __syncthreads();
;     if (kt + 1 < nk) {
;       u16* aw = As0 + ((kt + 1) & 1) * 256 * LD;
;       u16* bw = Bs0 + ((kt + 1) & 1) * 256 * LD;
; #pragma unroll
;       for (int i = 0; i < 4; ++i) { *(u32x4*)(aw + (srow + 64 * i) * LD + skc * 8) = ra[i]; *(u32x4*)(bw + (srow + 64 * i) * LD + skc * 8) = rb[i]; }
;     }
;     if (kt + 2 < nk) {
; #pragma unroll
;       for (int i = 0; i < 4; ++i) { ra[i] = *(const u32x4*)(Ag + (size_t)(64 * i) * K + (kt + 2) * 64); rb[i] = *(const u32x4*)(Bg[i] + (kt + 2) * 64); }
;     }
;     __builtin_amdgcn_sched_barrier(0);
;     const u16* as = As0 + (kt & 1) * 256 * LD + (wr * 128 + l31) * LD + h * 8;
;     const u16* bs = Bs0 + (kt & 1) * 256 * LD + (wc * 64 + l31) * LD + h * 8;
;     if (domma)
; #pragma unroll
;     for (int ks = 0; ks < 4; ++ks) {
;       bf16x8 wf[2], xf[4];
; #pragma unroll
;       for (int ct = 0; ct < 2; ++ct) wf[ct] = *(const bf16x8*)(bs + ct * 32 * LD + ks * 16);
; #pragma unroll
;       for (int tt = 0; tt < 4; ++tt) xf[tt] = *(const bf16x8*)(as + tt * 32 * LD + ks * 16);
; #pragma unroll
;       for (int ct = 0; ct < 2; ++ct)
; #pragma unroll
;         for (int tt = 0; tt < 4; ++tt) acc[ct][tt] = __builtin_amdgcn_mfma_f32_32x32x16_bf16(wf[ct], xf[tt], acc[ct][tt], 0, 0, 0);
;     }
;     __builtin_amdgcn_sched_barrier(0);
	ds_read_b128 v[210:213], v249
	ds_read_b128 v[236:239], v248
	ds_read_b128 v[214:217], v249 offset:4608
	ds_read_b128 v[2:5], v248 offset:4608
	ds_read_b128 v[6:9], v248 offset:9216
	ds_read_b128 v[10:13], v248 offset:13824
	s_waitcnt lgkmcnt(4)
	v_mfma_f32_32x32x16_bf16 v[114:129], v[210:213], v[236:239], v[114:129]
	ds_read_b128 v[228:231], v249 offset:32
	s_waitcnt lgkmcnt(4)
	v_mfma_f32_32x32x16_bf16 v[130:145], v[214:217], v[236:239], v[130:145]
	ds_read_b128 v[14:17], v248 offset:32
	s_waitcnt lgkmcnt(4)
	v_mfma_f32_32x32x16_bf16 v[82:97], v[210:213], v[2:5], v[82:97]
	ds_read_b128 v[232:235], v249 offset:4640
	v_mfma_f32_32x32x16_bf16 v[98:113], v[214:217], v[2:5], v[98:113]
	ds_read_b128 v[236:239], v248 offset:4640
	s_waitcnt vmcnt(15)
	ds_write_b128 v250, v[162:165] offset:36864
	s_waitcnt lgkmcnt(6)
	v_mfma_f32_32x32x16_bf16 v[50:65], v[210:213], v[6:9], v[50:65]
	ds_read_b128 v[2:5], v248 offset:9248
	v_mfma_f32_32x32x16_bf16 v[66:81], v[214:217], v[6:9], v[66:81]
	global_load_dwordx4 v[162:165], v227, s[74:75] offset:896
	s_waitcnt lgkmcnt(6)
	v_mfma_f32_32x32x16_bf16 v[18:33], v[210:213], v[10:13], v[18:33]
	ds_read_b128 v[6:9], v248 offset:13856
	s_waitcnt vmcnt(15)
	ds_write_b128 v251, v[194:197] offset:36864
	v_mfma_f32_32x32x16_bf16 v[34:49], v[214:217], v[10:13], v[34:49]
	s_waitcnt lgkmcnt(6)
	v_mfma_f32_32x32x16_bf16 v[114:129], v[228:231], v[14:17], v[114:129]
	ds_read_b128 v[210:213], v249 offset:64
	global_load_dwordx4 v[194:197], v227, s[82:83] offset:896
	s_waitcnt lgkmcnt(6)
	v_mfma_f32_32x32x16_bf16 v[130:145], v[232:235], v[14:17], v[130:145]
	ds_read_b128 v[10:13], v248 offset:64
	s_waitcnt vmcnt(15)
	ds_write_b128 v250, v[166:169] offset:46080
	s_waitcnt lgkmcnt(7)
	v_mfma_f32_32x32x16_bf16 v[82:97], v[228:231], v[236:239], v[82:97]
	ds_read_b128 v[214:217], v249 offset:4672
	v_mfma_f32_32x32x16_bf16 v[98:113], v[232:235], v[236:239], v[98:113]
	ds_read_b128 v[14:17], v248 offset:4672
	global_load_dwordx4 v[166:169], v227, s[76:77] offset:896
	s_waitcnt lgkmcnt(7)
	v_mfma_f32_32x32x16_bf16 v[50:65], v[228:231], v[2:5], v[50:65]
	ds_read_b128 v[236:239], v248 offset:9280
	s_waitcnt vmcnt(15)
	ds_write_b128 v251, v[198:201] offset:46080
	v_mfma_f32_32x32x16_bf16 v[66:81], v[232:235], v[2:5], v[66:81]
	s_waitcnt lgkmcnt(8)
	v_mfma_f32_32x32x16_bf16 v[18:33], v[228:231], v[6:9], v[18:33]
	ds_read_b128 v[2:5], v248 offset:13888
	global_load_dwordx4 v[198:201], v227, s[84:85] offset:896
	v_mfma_f32_32x32x16_bf16 v[34:49], v[232:235], v[6:9], v[34:49]
	s_waitcnt vmcnt(15)
	ds_write_b128 v250, v[170:173] offset:55296
	s_waitcnt lgkmcnt(7)
	v_mfma_f32_32x32x16_bf16 v[114:129], v[210:213], v[10:13], v[114:129]
	ds_read_b128 v[228:231], v249 offset:96
	s_waitcnt lgkmcnt(6)
	v_mfma_f32_32x32x16_bf16 v[130:145], v[214:217], v[10:13], v[130:145]
	ds_read_b128 v[6:9], v248 offset:96
	global_load_dwordx4 v[170:173], v227, s[78:79] offset:896
	s_waitcnt lgkmcnt(6)
	v_mfma_f32_32x32x16_bf16 v[82:97], v[210:213], v[14:17], v[82:97]
	ds_read_b128 v[232:235], v249 offset:4704
	s_waitcnt vmcnt(15)
	ds_write_b128 v251, v[202:205] offset:55296
	v_mfma_f32_32x32x16_bf16 v[98:113], v[214:217], v[14:17], v[98:113]
	ds_read_b128 v[10:13], v248 offset:4704
	s_waitcnt lgkmcnt(8)
	v_mfma_f32_32x32x16_bf16 v[50:65], v[210:213], v[236:239], v[50:65]
	ds_read_b128 v[14:17], v248 offset:9312
	global_load_dwordx4 v[202:205], v227, s[86:87] offset:896
	v_mfma_f32_32x32x16_bf16 v[66:81], v[214:217], v[236:239], v[66:81]
	s_waitcnt vmcnt(15)
	ds_write_b128 v250, v[174:177] offset:64512
	s_waitcnt lgkmcnt(8)
	v_mfma_f32_32x32x16_bf16 v[18:33], v[210:213], v[2:5], v[18:33]
	ds_read_b128 v[236:239], v248 offset:13920
	v_mfma_f32_32x32x16_bf16 v[34:49], v[214:217], v[2:5], v[34:49]
	global_load_dwordx4 v[174:177], v227, s[80:81] offset:896
	s_waitcnt lgkmcnt(6)
	v_mfma_f32_32x32x16_bf16 v[114:129], v[228:231], v[6:9], v[114:129]
	s_waitcnt vmcnt(15)
	ds_write_b128 v251, v[206:209] offset:64512
	s_waitcnt lgkmcnt(6)
	v_mfma_f32_32x32x16_bf16 v[130:145], v[232:235], v[6:9], v[130:145]
	s_waitcnt lgkmcnt(4)
	v_mfma_f32_32x32x16_bf16 v[82:97], v[228:231], v[10:13], v[82:97]
	global_load_dwordx4 v[206:209], v227, s[92:93] offset:896
	v_mfma_f32_32x32x16_bf16 v[98:113], v[232:235], v[10:13], v[98:113]
	s_waitcnt lgkmcnt(3)
	v_mfma_f32_32x32x16_bf16 v[50:65], v[228:231], v[14:17], v[50:65]
	v_mfma_f32_32x32x16_bf16 v[66:81], v[232:235], v[14:17], v[66:81]
	s_waitcnt lgkmcnt(1)
	v_mfma_f32_32x32x16_bf16 v[18:33], v[228:231], v[236:239], v[18:33]
	v_mfma_f32_32x32x16_bf16 v[34:49], v[232:235], v[236:239], v[34:49]
	s_waitcnt lgkmcnt(0)
	s_barrier
;     ...
;   for (int kt = 0; kt < nk; ++kt) {
;     __syncthreads();
;     if (kt + 1 < nk) {
;       u16* aw = As0 + ((kt + 1) & 1) * 256 * LD;
;       u16* bw = Bs0 + ((kt + 1) & 1) * 256 * LD;
; #pragma unroll
;       for (int i = 0; i < 4; ++i) { *(u32x4*)(aw + (srow + 64 * i) * LD + skc * 8) = ra[i]; *(u32x4*)(bw + (srow + 64 * i) * LD + skc * 8) = rb[i]; }
;     }
;     if (kt + 2 < nk) {
; #pragma unroll
;       for (int i = 0; i < 4; ++i) { ra[i] = *(const u32x4*)(Ag + (size_t)(64 * i) * K + (kt + 2) * 64); rb[i] = *(const u32x4*)(Bg[i] + (kt + 2) * 64); }
;     }
;     __builtin_amdgcn_sched_barrier(0);
;     const u16* as = As0 + (kt & 1) * 256 * LD + (wr * 128 + l31) * LD + h * 8;
;     const u16* bs = Bs0 + (kt & 1) * 256 * LD + (wc * 64 + l31) * LD + h * 8;
;     if (domma)
; #pragma unroll
;     for (int ks = 0; ks < 4; ++ks) {
;       bf16x8 wf[2], xf[4];
; #pragma unroll
;       for (int ct = 0; ct < 2; ++ct) wf[ct] = *(const bf16x8*)(bs + ct * 32 * LD + ks * 16);
; #pragma unroll
;       for (int tt = 0; tt < 4; ++tt) xf[tt] = *(const bf16x8*)(as + tt * 32 * LD + ks * 16);
; #pragma unroll
;       for (int ct = 0; ct < 2; ++ct)
; #pragma unroll
;         for (int tt = 0; tt < 4; ++tt) acc[ct][tt] = __builtin_amdgcn_mfma_f32_32x32x16_bf16(wf[ct], xf[tt], acc[ct][tt], 0, 0, 0);
;     }
;     __builtin_amdgcn_sched_barrier(0);
	ds_read_b128 v[210:213], v249 offset:36864
	ds_read_b128 v[236:239], v248 offset:36864
	ds_read_b128 v[214:217], v249 offset:41472
	ds_read_b128 v[2:5], v248 offset:41472
	ds_read_b128 v[6:9], v248 offset:46080
	ds_read_b128 v[10:13], v248 offset:50688
	s_waitcnt lgkmcnt(4)
	v_mfma_f32_32x32x16_bf16 v[114:129], v[210:213], v[236:239], v[114:129]
	ds_read_b128 v[228:231], v249 offset:36896
	s_waitcnt lgkmcnt(4)
	v_mfma_f32_32x32x16_bf16 v[130:145], v[214:217], v[236:239], v[130:145]
	ds_read_b128 v[14:17], v248 offset:36896
	s_waitcnt lgkmcnt(4)
	v_mfma_f32_32x32x16_bf16 v[82:97], v[210:213], v[2:5], v[82:97]
	ds_read_b128 v[232:235], v249 offset:41504
	v_mfma_f32_32x32x16_bf16 v[98:113], v[214:217], v[2:5], v[98:113]
	ds_read_b128 v[236:239], v248 offset:41504
	s_waitcnt vmcnt(15)
	ds_write_b128 v250, v[146:149]
	s_waitcnt lgkmcnt(6)
	v_mfma_f32_32x32x16_bf16 v[50:65], v[210:213], v[6:9], v[50:65]
	ds_read_b128 v[2:5], v248 offset:46112
	v_mfma_f32_32x32x16_bf16 v[66:81], v[214:217], v[6:9], v[66:81]
	global_load_dwordx4 v[146:149], v227, s[74:75] offset:1024
	s_waitcnt lgkmcnt(6)
	v_mfma_f32_32x32x16_bf16 v[18:33], v[210:213], v[10:13], v[18:33]
	ds_read_b128 v[6:9], v248 offset:50720
	s_waitcnt vmcnt(15)
	ds_write_b128 v251, v[178:181]
	v_mfma_f32_32x32x16_bf16 v[34:49], v[214:217], v[10:13], v[34:49]
	s_waitcnt lgkmcnt(6)
	v_mfma_f32_32x32x16_bf16 v[114:129], v[228:231], v[14:17], v[114:129]
	ds_read_b128 v[210:213], v249 offset:36928
	global_load_dwordx4 v[178:181], v227, s[82:83] offset:1024
	s_waitcnt lgkmcnt(6)
	v_mfma_f32_32x32x16_bf16 v[130:145], v[232:235], v[14:17], v[130:145]
	ds_read_b128 v[10:13], v248 offset:36928
	s_waitcnt vmcnt(15)
	ds_write_b128 v250, v[150:153] offset:9216
	s_waitcnt lgkmcnt(7)
	v_mfma_f32_32x32x16_bf16 v[82:97], v[228:231], v[236:239], v[82:97]
	ds_read_b128 v[214:217], v249 offset:41536
	v_mfma_f32_32x32x16_bf16 v[98:113], v[232:235], v[236:239], v[98:113]
	ds_read_b128 v[14:17], v248 offset:41536
	global_load_dwordx4 v[150:153], v227, s[76:77] offset:1024
	s_waitcnt lgkmcnt(7)
	v_mfma_f32_32x32x16_bf16 v[50:65], v[228:231], v[2:5], v[50:65]
	ds_read_b128 v[236:239], v248 offset:46144
	s_waitcnt vmcnt(15)
	ds_write_b128 v251, v[182:185] offset:9216
	v_mfma_f32_32x32x16_bf16 v[66:81], v[232:235], v[2:5], v[66:81]
	s_waitcnt lgkmcnt(8)
	v_mfma_f32_32x32x16_bf16 v[18:33], v[228:231], v[6:9], v[18:33]
	ds_read_b128 v[2:5], v248 offset:50752
	global_load_dwordx4 v[182:185], v227, s[84:85] offset:1024
	v_mfma_f32_32x32x16_bf16 v[34:49], v[232:235], v[6:9], v[34:49]
	s_waitcnt vmcnt(15)
	ds_write_b128 v250, v[154:157] offset:18432
	s_waitcnt lgkmcnt(7)
	v_mfma_f32_32x32x16_bf16 v[114:129], v[210:213], v[10:13], v[114:129]
	ds_read_b128 v[228:231], v249 offset:36960
	s_waitcnt lgkmcnt(6)
	v_mfma_f32_32x32x16_bf16 v[130:145], v[214:217], v[10:13], v[130:145]
	ds_read_b128 v[6:9], v248 offset:36960
	global_load_dwordx4 v[154:157], v227, s[78:79] offset:1024
	s_waitcnt lgkmcnt(6)
	v_mfma_f32_32x32x16_bf16 v[82:97], v[210:213], v[14:17], v[82:97]
	ds_read_b128 v[232:235], v249 offset:41568
	s_waitcnt vmcnt(15)
	ds_write_b128 v251, v[186:189] offset:18432
	v_mfma_f32_32x32x16_bf16 v[98:113], v[214:217], v[14:17], v[98:113]
	ds_read_b128 v[10:13], v248 offset:41568
	s_waitcnt lgkmcnt(8)
	v_mfma_f32_32x32x16_bf16 v[50:65], v[210:213], v[236:239], v[50:65]
	ds_read_b128 v[14:17], v248 offset:46176
	global_load_dwordx4 v[186:189], v227, s[86:87] offset:1024
	v_mfma_f32_32x32x16_bf16 v[66:81], v[214:217], v[236:239], v[66:81]
	s_waitcnt vmcnt(15)
	ds_write_b128 v250, v[158:161] offset:27648
	s_waitcnt lgkmcnt(8)
	v_mfma_f32_32x32x16_bf16 v[18:33], v[210:213], v[2:5], v[18:33]
	ds_read_b128 v[236:239], v248 offset:50784
	v_mfma_f32_32x32x16_bf16 v[34:49], v[214:217], v[2:5], v[34:49]
	global_load_dwordx4 v[158:161], v227, s[80:81] offset:1024
	s_waitcnt lgkmcnt(6)
	v_mfma_f32_32x32x16_bf16 v[114:129], v[228:231], v[6:9], v[114:129]
	s_waitcnt vmcnt(15)
	ds_write_b128 v251, v[190:193] offset:27648
	s_waitcnt lgkmcnt(6)
	v_mfma_f32_32x32x16_bf16 v[130:145], v[232:235], v[6:9], v[130:145]
	s_waitcnt lgkmcnt(4)
	v_mfma_f32_32x32x16_bf16 v[82:97], v[228:231], v[10:13], v[82:97]
	global_load_dwordx4 v[190:193], v227, s[92:93] offset:1024
	v_mfma_f32_32x32x16_bf16 v[98:113], v[232:235], v[10:13], v[98:113]
	s_waitcnt lgkmcnt(3)
	v_mfma_f32_32x32x16_bf16 v[50:65], v[228:231], v[14:17], v[50:65]
	v_mfma_f32_32x32x16_bf16 v[66:81], v[232:235], v[14:17], v[66:81]
	s_waitcnt lgkmcnt(1)
	v_mfma_f32_32x32x16_bf16 v[18:33], v[228:231], v[236:239], v[18:33]
	v_mfma_f32_32x32x16_bf16 v[34:49], v[232:235], v[236:239], v[34:49]
	s_waitcnt lgkmcnt(0)
	s_barrier
;     ...
;   for (int kt = 0; kt < nk; ++kt) {
;     __syncthreads();
;     if (kt + 1 < nk) {
;       u16* aw = As0 + ((kt + 1) & 1) * 256 * LD;
;       u16* bw = Bs0 + ((kt + 1) & 1) * 256 * LD;
; #pragma unroll
;       for (int i = 0; i < 4; ++i) { *(u32x4*)(aw + (srow + 64 * i) * LD + skc * 8) = ra[i]; *(u32x4*)(bw + (srow + 64 * i) * LD + skc * 8) = rb[i]; }
;     }
;     if (kt + 2 < nk) {
; #pragma unroll
;       for (int i = 0; i < 4; ++i) { ra[i] = *(const u32x4*)(Ag + (size_t)(64 * i) * K + (kt + 2) * 64); rb[i] = *(const u32x4*)(Bg[i] + (kt + 2) * 64); }
;     }
;     __builtin_amdgcn_sched_barrier(0);
;     const u16* as = As0 + (kt & 1) * 256 * LD + (wr * 128 + l31) * LD + h * 8;
;     const u16* bs = Bs0 + (kt & 1) * 256 * LD + (wc * 64 + l31) * LD + h * 8;
;     if (domma)
; #pragma unroll
;     for (int ks = 0; ks < 4; ++ks) {
;       bf16x8 wf[2], xf[4];
; #pragma unroll
;       for (int ct = 0; ct < 2; ++ct) wf[ct] = *(const bf16x8*)(bs + ct * 32 * LD + ks * 16);
; #pragma unroll
;       for (int tt = 0; tt < 4; ++tt) xf[tt] = *(const bf16x8*)(as + tt * 32 * LD + ks * 16);
; #pragma unroll
;       for (int ct = 0; ct < 2; ++ct)
; #pragma unroll
;         for (int tt = 0; tt < 4; ++tt) acc[ct][tt] = __builtin_amdgcn_mfma_f32_32x32x16_bf16(wf[ct], xf[tt], acc[ct][tt], 0, 0, 0);
;     }
;     __builtin_amdgcn_sched_barrier(0);
	ds_read_b128 v[210:213], v249
	ds_read_b128 v[236:239], v248
	ds_read_b128 v[214:217], v249 offset:4608
	ds_read_b128 v[2:5], v248 offset:4608
	ds_read_b128 v[6:9], v248 offset:9216
	ds_read_b128 v[10:13], v248 offset:13824
	s_waitcnt lgkmcnt(4)
	v_mfma_f32_32x32x16_bf16 v[114:129], v[210:213], v[236:239], v[114:129]
	ds_read_b128 v[228:231], v249 offset:32
	s_waitcnt lgkmcnt(4)
	v_mfma_f32_32x32x16_bf16 v[130:145], v[214:217], v[236:239], v[130:145]
	ds_read_b128 v[14:17], v248 offset:32
	s_waitcnt lgkmcnt(4)
	v_mfma_f32_32x32x16_bf16 v[82:97], v[210:213], v[2:5], v[82:97]
	ds_read_b128 v[232:235], v249 offset:4640
	v_mfma_f32_32x32x16_bf16 v[98:113], v[214:217], v[2:5], v[98:113]
	ds_read_b128 v[236:239], v248 offset:4640
	s_waitcnt vmcnt(15)
	ds_write_b128 v250, v[162:165] offset:36864
	s_waitcnt lgkmcnt(6)
	v_mfma_f32_32x32x16_bf16 v[50:65], v[210:213], v[6:9], v[50:65]
	ds_read_b128 v[2:5], v248 offset:9248
	v_mfma_f32_32x32x16_bf16 v[66:81], v[214:217], v[6:9], v[66:81]
	global_load_dwordx4 v[162:165], v227, s[74:75] offset:1152
	s_waitcnt lgkmcnt(6)
	v_mfma_f32_32x32x16_bf16 v[18:33], v[210:213], v[10:13], v[18:33]
	ds_read_b128 v[6:9], v248 offset:13856
	s_waitcnt vmcnt(15)
	ds_write_b128 v251, v[194:197] offset:36864
	v_mfma_f32_32x32x16_bf16 v[34:49], v[214:217], v[10:13], v[34:49]
	s_waitcnt lgkmcnt(6)
	v_mfma_f32_32x32x16_bf16 v[114:129], v[228:231], v[14:17], v[114:129]
	ds_read_b128 v[210:213], v249 offset:64
	global_load_dwordx4 v[194:197], v227, s[82:83] offset:1152
	s_waitcnt lgkmcnt(6)
	v_mfma_f32_32x32x16_bf16 v[130:145], v[232:235], v[14:17], v[130:145]
	ds_read_b128 v[10:13], v248 offset:64
	s_waitcnt vmcnt(15)
	ds_write_b128 v250, v[166:169] offset:46080
	s_waitcnt lgkmcnt(7)
	v_mfma_f32_32x32x16_bf16 v[82:97], v[228:231], v[236:239], v[82:97]
	ds_read_b128 v[214:217], v249 offset:4672
	v_mfma_f32_32x32x16_bf16 v[98:113], v[232:235], v[236:239], v[98:113]
	ds_read_b128 v[14:17], v248 offset:4672
	global_load_dwordx4 v[166:169], v227, s[76:77] offset:1152
	s_waitcnt lgkmcnt(7)
	v_mfma_f32_32x32x16_bf16 v[50:65], v[228:231], v[2:5], v[50:65]
	ds_read_b128 v[236:239], v248 offset:9280
	s_waitcnt vmcnt(15)
	ds_write_b128 v251, v[198:201] offset:46080
	v_mfma_f32_32x32x16_bf16 v[66:81], v[232:235], v[2:5], v[66:81]
	s_waitcnt lgkmcnt(8)
	v_mfma_f32_32x32x16_bf16 v[18:33], v[228:231], v[6:9], v[18:33]
	ds_read_b128 v[2:5], v248 offset:13888
	global_load_dwordx4 v[198:201], v227, s[84:85] offset:1152
	v_mfma_f32_32x32x16_bf16 v[34:49], v[232:235], v[6:9], v[34:49]
	s_waitcnt vmcnt(15)
	ds_write_b128 v250, v[170:173] offset:55296
	s_waitcnt lgkmcnt(7)
	v_mfma_f32_32x32x16_bf16 v[114:129], v[210:213], v[10:13], v[114:129]
	ds_read_b128 v[228:231], v249 offset:96
	s_waitcnt lgkmcnt(6)
	v_mfma_f32_32x32x16_bf16 v[130:145], v[214:217], v[10:13], v[130:145]
	ds_read_b128 v[6:9], v248 offset:96
	global_load_dwordx4 v[170:173], v227, s[78:79] offset:1152
	s_waitcnt lgkmcnt(6)
	v_mfma_f32_32x32x16_bf16 v[82:97], v[210:213], v[14:17], v[82:97]
	ds_read_b128 v[232:235], v249 offset:4704
	s_waitcnt vmcnt(15)
	ds_write_b128 v251, v[202:205] offset:55296
	v_mfma_f32_32x32x16_bf16 v[98:113], v[214:217], v[14:17], v[98:113]
	ds_read_b128 v[10:13], v248 offset:4704
	s_waitcnt lgkmcnt(8)
	v_mfma_f32_32x32x16_bf16 v[50:65], v[210:213], v[236:239], v[50:65]
	ds_read_b128 v[14:17], v248 offset:9312
	global_load_dwordx4 v[202:205], v227, s[86:87] offset:1152
	v_mfma_f32_32x32x16_bf16 v[66:81], v[214:217], v[236:239], v[66:81]
	s_waitcnt vmcnt(15)
	ds_write_b128 v250, v[174:177] offset:64512
	s_waitcnt lgkmcnt(8)
	v_mfma_f32_32x32x16_bf16 v[18:33], v[210:213], v[2:5], v[18:33]
	ds_read_b128 v[236:239], v248 offset:13920
	v_mfma_f32_32x32x16_bf16 v[34:49], v[214:217], v[2:5], v[34:49]
	global_load_dwordx4 v[174:177], v227, s[80:81] offset:1152
	s_waitcnt lgkmcnt(6)
	v_mfma_f32_32x32x16_bf16 v[114:129], v[228:231], v[6:9], v[114:129]
	s_waitcnt vmcnt(15)
	ds_write_b128 v251, v[206:209] offset:64512
	s_waitcnt lgkmcnt(6)
	v_mfma_f32_32x32x16_bf16 v[130:145], v[232:235], v[6:9], v[130:145]
	s_waitcnt lgkmcnt(4)
	v_mfma_f32_32x32x16_bf16 v[82:97], v[228:231], v[10:13], v[82:97]
	global_load_dwordx4 v[206:209], v227, s[92:93] offset:1152
	v_mfma_f32_32x32x16_bf16 v[98:113], v[232:235], v[10:13], v[98:113]
	s_waitcnt lgkmcnt(3)
	v_mfma_f32_32x32x16_bf16 v[50:65], v[228:231], v[14:17], v[50:65]
	v_mfma_f32_32x32x16_bf16 v[66:81], v[232:235], v[14:17], v[66:81]
	s_waitcnt lgkmcnt(1)
	v_mfma_f32_32x32x16_bf16 v[18:33], v[228:231], v[236:239], v[18:33]
	v_mfma_f32_32x32x16_bf16 v[34:49], v[232:235], v[236:239], v[34:49]
	s_waitcnt lgkmcnt(0)
	s_barrier
;     ...
;   for (int kt = 0; kt < nk; ++kt) {
;     __syncthreads();
;     if (kt + 1 < nk) {
;       u16* aw = As0 + ((kt + 1) & 1) * 256 * LD;
;       u16* bw = Bs0 + ((kt + 1) & 1) * 256 * LD;
; #pragma unroll
;       for (int i = 0; i < 4; ++i) { *(u32x4*)(aw + (srow + 64 * i) * LD + skc * 8) = ra[i]; *(u32x4*)(bw + (srow + 64 * i) * LD + skc * 8) = rb[i]; }
;     }
;     if (kt + 2 < nk) {
; #pragma unroll
;       for (int i = 0; i < 4; ++i) { ra[i] = *(const u32x4*)(Ag + (size_t)(64 * i) * K + (kt + 2) * 64); rb[i] = *(const u32x4*)(Bg[i] + (kt + 2) * 64); }
;     }
;     __builtin_amdgcn_sched_barrier(0);
;     const u16* as = As0 + (kt & 1) * 256 * LD + (wr * 128 + l31) * LD + h * 8;
;     const u16* bs = Bs0 + (kt & 1) * 256 * LD + (wc * 64 + l31) * LD + h * 8;
;     if (domma)
; #pragma unroll
;     for (int ks = 0; ks < 4; ++ks) {
;       bf16x8 wf[2], xf[4];
; #pragma unroll
;       for (int ct = 0; ct < 2; ++ct) wf[ct] = *(const bf16x8*)(bs + ct * 32 * LD + ks * 16);
; #pragma unroll
;       for (int tt = 0; tt < 4; ++tt) xf[tt] = *(const bf16x8*)(as + tt * 32 * LD + ks * 16);
; #pragma unroll
;       for (int ct = 0; ct < 2; ++ct)
; #pragma unroll
;         for (int tt = 0; tt < 4; ++tt) acc[ct][tt] = __builtin_amdgcn_mfma_f32_32x32x16_bf16(wf[ct], xf[tt], acc[ct][tt], 0, 0, 0);
;     }
;     __builtin_amdgcn_sched_barrier(0);
;   }
	ds_read_b128 v[210:213], v249 offset:36864
	ds_read_b128 v[236:239], v248 offset:36864
	ds_read_b128 v[214:217], v249 offset:41472
	ds_read_b128 v[2:5], v248 offset:41472
	ds_read_b128 v[6:9], v248 offset:46080
	ds_read_b128 v[10:13], v248 offset:50688
	s_waitcnt lgkmcnt(4)
	v_mfma_f32_32x32x16_bf16 v[114:129], v[210:213], v[236:239], v[114:129]
	ds_read_b128 v[228:231], v249 offset:36896
	s_waitcnt lgkmcnt(4)
	v_mfma_f32_32x32x16_bf16 v[130:145], v[214:217], v[236:239], v[130:145]
	ds_read_b128 v[14:17], v248 offset:36896
	s_waitcnt lgkmcnt(4)
	v_mfma_f32_32x32x16_bf16 v[82:97], v[210:213], v[2:5], v[82:97]
	ds_read_b128 v[232:235], v249 offset:41504
	v_mfma_f32_32x32x16_bf16 v[98:113], v[214:217], v[2:5], v[98:113]
	ds_read_b128 v[236:239], v248 offset:41504
	s_waitcnt vmcnt(15)
	ds_write_b128 v250, v[146:149]
	s_waitcnt lgkmcnt(6)
	v_mfma_f32_32x32x16_bf16 v[50:65], v[210:213], v[6:9], v[50:65]
	ds_read_b128 v[2:5], v248 offset:46112
	v_mfma_f32_32x32x16_bf16 v[66:81], v[214:217], v[6:9], v[66:81]
	global_load_dwordx4 v[146:149], v227, s[74:75] offset:1280
	s_waitcnt lgkmcnt(6)
	v_mfma_f32_32x32x16_bf16 v[18:33], v[210:213], v[10:13], v[18:33]
	ds_read_b128 v[6:9], v248 offset:50720
	s_waitcnt vmcnt(15)
	ds_write_b128 v251, v[178:181]
	v_mfma_f32_32x32x16_bf16 v[34:49], v[214:217], v[10:13], v[34:49]
	s_waitcnt lgkmcnt(6)
	v_mfma_f32_32x32x16_bf16 v[114:129], v[228:231], v[14:17], v[114:129]
	ds_read_b128 v[210:213], v249 offset:36928
	global_load_dwordx4 v[178:181], v227, s[82:83] offset:1280
	s_waitcnt lgkmcnt(6)
	v_mfma_f32_32x32x16_bf16 v[130:145], v[232:235], v[14:17], v[130:145]
	ds_read_b128 v[10:13], v248 offset:36928
	s_waitcnt vmcnt(15)
	ds_write_b128 v250, v[150:153] offset:9216
	s_waitcnt lgkmcnt(7)
	v_mfma_f32_32x32x16_bf16 v[82:97], v[228:231], v[236:239], v[82:97]
	ds_read_b128 v[214:217], v249 offset:41536
	v_mfma_f32_32x32x16_bf16 v[98:113], v[232:235], v[236:239], v[98:113]
	ds_read_b128 v[14:17], v248 offset:41536
	global_load_dwordx4 v[150:153], v227, s[76:77] offset:1280
	s_waitcnt lgkmcnt(7)
	v_mfma_f32_32x32x16_bf16 v[50:65], v[228:231], v[2:5], v[50:65]
	ds_read_b128 v[236:239], v248 offset:46144
	s_waitcnt vmcnt(15)
	ds_write_b128 v251, v[182:185] offset:9216
	v_mfma_f32_32x32x16_bf16 v[66:81], v[232:235], v[2:5], v[66:81]
	s_waitcnt lgkmcnt(8)
	v_mfma_f32_32x32x16_bf16 v[18:33], v[228:231], v[6:9], v[18:33]
	ds_read_b128 v[2:5], v248 offset:50752
	global_load_dwordx4 v[182:185], v227, s[84:85] offset:1280
	v_mfma_f32_32x32x16_bf16 v[34:49], v[232:235], v[6:9], v[34:49]
	s_waitcnt vmcnt(15)
	ds_write_b128 v250, v[154:157] offset:18432
	s_waitcnt lgkmcnt(7)
	v_mfma_f32_32x32x16_bf16 v[114:129], v[210:213], v[10:13], v[114:129]
	ds_read_b128 v[228:231], v249 offset:36960
	s_waitcnt lgkmcnt(6)
	v_mfma_f32_32x32x16_bf16 v[130:145], v[214:217], v[10:13], v[130:145]
	ds_read_b128 v[6:9], v248 offset:36960
	global_load_dwordx4 v[154:157], v227, s[78:79] offset:1280
	s_waitcnt lgkmcnt(6)
	v_mfma_f32_32x32x16_bf16 v[82:97], v[210:213], v[14:17], v[82:97]
	ds_read_b128 v[232:235], v249 offset:41568
	s_waitcnt vmcnt(15)
	ds_write_b128 v251, v[186:189] offset:18432
	v_mfma_f32_32x32x16_bf16 v[98:113], v[214:217], v[14:17], v[98:113]
	ds_read_b128 v[10:13], v248 offset:41568
	s_waitcnt lgkmcnt(8)
	v_mfma_f32_32x32x16_bf16 v[50:65], v[210:213], v[236:239], v[50:65]
	ds_read_b128 v[14:17], v248 offset:46176
	global_load_dwordx4 v[186:189], v227, s[86:87] offset:1280
	v_mfma_f32_32x32x16_bf16 v[66:81], v[214:217], v[236:239], v[66:81]
	s_waitcnt vmcnt(15)
	ds_write_b128 v250, v[158:161] offset:27648
	s_waitcnt lgkmcnt(8)
	v_mfma_f32_32x32x16_bf16 v[18:33], v[210:213], v[2:5], v[18:33]
	ds_read_b128 v[236:239], v248 offset:50784
	v_mfma_f32_32x32x16_bf16 v[34:49], v[214:217], v[2:5], v[34:49]
	global_load_dwordx4 v[158:161], v227, s[80:81] offset:1280
	s_waitcnt lgkmcnt(6)
	v_mfma_f32_32x32x16_bf16 v[114:129], v[228:231], v[6:9], v[114:129]
	s_waitcnt vmcnt(15)
	ds_write_b128 v251, v[190:193] offset:27648
	s_waitcnt lgkmcnt(6)
	v_mfma_f32_32x32x16_bf16 v[130:145], v[232:235], v[6:9], v[130:145]
	s_waitcnt lgkmcnt(4)
	v_mfma_f32_32x32x16_bf16 v[82:97], v[228:231], v[10:13], v[82:97]
	global_load_dwordx4 v[190:193], v227, s[92:93] offset:1280
	v_mfma_f32_32x32x16_bf16 v[98:113], v[232:235], v[10:13], v[98:113]
	s_waitcnt lgkmcnt(3)
	v_mfma_f32_32x32x16_bf16 v[50:65], v[228:231], v[14:17], v[50:65]
	v_mfma_f32_32x32x16_bf16 v[66:81], v[232:235], v[14:17], v[66:81]
	s_waitcnt lgkmcnt(1)
	v_mfma_f32_32x32x16_bf16 v[18:33], v[228:231], v[236:239], v[18:33]
	v_mfma_f32_32x32x16_bf16 v[34:49], v[232:235], v[236:239], v[34:49]
	s_waitcnt lgkmcnt(0)
	s_barrier
;     ...
;   for (int kt = 0; kt < nk; ++kt) {
;     __syncthreads();
;     if (kt + 1 < nk) {
;       u16* aw = As0 + ((kt + 1) & 1) * 256 * LD;
;       u16* bw = Bs0 + ((kt + 1) & 1) * 256 * LD;
; #pragma unroll
;       for (int i = 0; i < 4; ++i) { *(u32x4*)(aw + (srow + 64 * i) * LD + skc * 8) = ra[i]; *(u32x4*)(bw + (srow + 64 * i) * LD + skc * 8) = rb[i]; }
;     }
;     if (kt + 2 < nk) {
; #pragma unroll
;       for (int i = 0; i < 4; ++i) { ra[i] = *(const u32x4*)(Ag + (size_t)(64 * i) * K + (kt + 2) * 64); rb[i] = *(const u32x4*)(Bg[i] + (kt + 2) * 64); }
;     }
;     __builtin_amdgcn_sched_barrier(0);
;     const u16* as = As0 + (kt & 1) * 256 * LD + (wr * 128 + l31) * LD + h * 8;
;     const u16* bs = Bs0 + (kt & 1) * 256 * LD + (wc * 64 + l31) * LD + h * 8;
;     if (domma)
; #pragma unroll
;     for (int ks = 0; ks < 4; ++ks) {
;       bf16x8 wf[2], xf[4];
; #pragma unroll
;       for (int ct = 0; ct < 2; ++ct) wf[ct] = *(const bf16x8*)(bs + ct * 32 * LD + ks * 16);
; #pragma unroll
;       for (int tt = 0; tt < 4; ++tt) xf[tt] = *(const bf16x8*)(as + tt * 32 * LD + ks * 16);
; #pragma unroll
;       for (int ct = 0; ct < 2; ++ct)
; #pragma unroll
;         for (int tt = 0; tt < 4; ++tt) acc[ct][tt] = __builtin_amdgcn_mfma_f32_32x32x16_bf16(wf[ct], xf[tt], acc[ct][tt], 0, 0, 0);
;     }
;     __builtin_amdgcn_sched_barrier(0);
;   }
	ds_read_b128 v[210:213], v249
	ds_read_b128 v[236:239], v248
	ds_read_b128 v[214:217], v249 offset:4608
	ds_read_b128 v[2:5], v248 offset:4608
	ds_read_b128 v[6:9], v248 offset:9216
	ds_read_b128 v[10:13], v248 offset:13824
	s_waitcnt lgkmcnt(4)
	v_mfma_f32_32x32x16_bf16 v[114:129], v[210:213], v[236:239], v[114:129]
	ds_read_b128 v[228:231], v249 offset:32
	s_waitcnt lgkmcnt(4)
	v_mfma_f32_32x32x16_bf16 v[130:145], v[214:217], v[236:239], v[130:145]
	ds_read_b128 v[14:17], v248 offset:32
	s_waitcnt lgkmcnt(4)
	v_mfma_f32_32x32x16_bf16 v[82:97], v[210:213], v[2:5], v[82:97]
	ds_read_b128 v[232:235], v249 offset:4640
	v_mfma_f32_32x32x16_bf16 v[98:113], v[214:217], v[2:5], v[98:113]
	ds_read_b128 v[236:239], v248 offset:4640
	s_waitcnt vmcnt(15)
	ds_write_b128 v250, v[162:165] offset:36864
	s_waitcnt lgkmcnt(6)
	v_mfma_f32_32x32x16_bf16 v[50:65], v[210:213], v[6:9], v[50:65]
	ds_read_b128 v[2:5], v248 offset:9248
	v_mfma_f32_32x32x16_bf16 v[66:81], v[214:217], v[6:9], v[66:81]
	global_load_dwordx4 v[162:165], v227, s[74:75] offset:1408
	s_waitcnt lgkmcnt(6)
	v_mfma_f32_32x32x16_bf16 v[18:33], v[210:213], v[10:13], v[18:33]
	ds_read_b128 v[6:9], v248 offset:13856
	s_waitcnt vmcnt(15)
	ds_write_b128 v251, v[194:197] offset:36864
	v_mfma_f32_32x32x16_bf16 v[34:49], v[214:217], v[10:13], v[34:49]
	s_waitcnt lgkmcnt(6)
	v_mfma_f32_32x32x16_bf16 v[114:129], v[228:231], v[14:17], v[114:129]
	ds_read_b128 v[210:213], v249 offset:64
	global_load_dwordx4 v[194:197], v227, s[82:83] offset:1408
	s_waitcnt lgkmcnt(6)
	v_mfma_f32_32x32x16_bf16 v[130:145], v[232:235], v[14:17], v[130:145]
	ds_read_b128 v[10:13], v248 offset:64
	s_waitcnt vmcnt(15)
	ds_write_b128 v250, v[166:169] offset:46080
	s_waitcnt lgkmcnt(7)
	v_mfma_f32_32x32x16_bf16 v[82:97], v[228:231], v[236:239], v[82:97]
	ds_read_b128 v[214:217], v249 offset:4672
	v_mfma_f32_32x32x16_bf16 v[98:113], v[232:235], v[236:239], v[98:113]
	ds_read_b128 v[14:17], v248 offset:4672
	global_load_dwordx4 v[166:169], v227, s[76:77] offset:1408
	s_waitcnt lgkmcnt(7)
	v_mfma_f32_32x32x16_bf16 v[50:65], v[228:231], v[2:5], v[50:65]
	ds_read_b128 v[236:239], v248 offset:9280
	s_waitcnt vmcnt(15)
	ds_write_b128 v251, v[198:201] offset:46080
	v_mfma_f32_32x32x16_bf16 v[66:81], v[232:235], v[2:5], v[66:81]
	s_waitcnt lgkmcnt(8)
	v_mfma_f32_32x32x16_bf16 v[18:33], v[228:231], v[6:9], v[18:33]
	ds_read_b128 v[2:5], v248 offset:13888
	global_load_dwordx4 v[198:201], v227, s[84:85] offset:1408
	v_mfma_f32_32x32x16_bf16 v[34:49], v[232:235], v[6:9], v[34:49]
	s_waitcnt vmcnt(15)
	ds_write_b128 v250, v[170:173] offset:55296
	s_waitcnt lgkmcnt(7)
	v_mfma_f32_32x32x16_bf16 v[114:129], v[210:213], v[10:13], v[114:129]
	ds_read_b128 v[228:231], v249 offset:96
	s_waitcnt lgkmcnt(6)
	v_mfma_f32_32x32x16_bf16 v[130:145], v[214:217], v[10:13], v[130:145]
	ds_read_b128 v[6:9], v248 offset:96
	global_load_dwordx4 v[170:173], v227, s[78:79] offset:1408
	s_waitcnt lgkmcnt(6)
	v_mfma_f32_32x32x16_bf16 v[82:97], v[210:213], v[14:17], v[82:97]
	ds_read_b128 v[232:235], v249 offset:4704
	s_waitcnt vmcnt(15)
	ds_write_b128 v251, v[202:205] offset:55296
	v_mfma_f32_32x32x16_bf16 v[98:113], v[214:217], v[14:17], v[98:113]
	ds_read_b128 v[10:13], v248 offset:4704
	s_waitcnt lgkmcnt(8)
	v_mfma_f32_32x32x16_bf16 v[50:65], v[210:213], v[236:239], v[50:65]
	ds_read_b128 v[14:17], v248 offset:9312
	global_load_dwordx4 v[202:205], v227, s[86:87] offset:1408
	v_mfma_f32_32x32x16_bf16 v[66:81], v[214:217], v[236:239], v[66:81]
	s_waitcnt vmcnt(15)
	ds_write_b128 v250, v[174:177] offset:64512
	s_waitcnt lgkmcnt(8)
	v_mfma_f32_32x32x16_bf16 v[18:33], v[210:213], v[2:5], v[18:33]
	ds_read_b128 v[236:239], v248 offset:13920
	v_mfma_f32_32x32x16_bf16 v[34:49], v[214:217], v[2:5], v[34:49]
	global_load_dwordx4 v[174:177], v227, s[80:81] offset:1408
	s_waitcnt lgkmcnt(6)
	v_mfma_f32_32x32x16_bf16 v[114:129], v[228:231], v[6:9], v[114:129]
	s_waitcnt vmcnt(15)
	ds_write_b128 v251, v[206:209] offset:64512
	s_waitcnt lgkmcnt(6)
	v_mfma_f32_32x32x16_bf16 v[130:145], v[232:235], v[6:9], v[130:145]
	s_waitcnt lgkmcnt(4)
	v_mfma_f32_32x32x16_bf16 v[82:97], v[228:231], v[10:13], v[82:97]
	global_load_dwordx4 v[206:209], v227, s[92:93] offset:1408
	v_mfma_f32_32x32x16_bf16 v[98:113], v[232:235], v[10:13], v[98:113]
	s_waitcnt lgkmcnt(3)
	v_mfma_f32_32x32x16_bf16 v[50:65], v[228:231], v[14:17], v[50:65]
	v_mfma_f32_32x32x16_bf16 v[66:81], v[232:235], v[14:17], v[66:81]
	s_waitcnt lgkmcnt(1)
	v_mfma_f32_32x32x16_bf16 v[18:33], v[228:231], v[236:239], v[18:33]
	v_mfma_f32_32x32x16_bf16 v[34:49], v[232:235], v[236:239], v[34:49]
	s_waitcnt lgkmcnt(0)
	s_barrier
;     ...
;   for (int kt = 0; kt < nk; ++kt) {
;     __syncthreads();
;     if (kt + 1 < nk) {
;       u16* aw = As0 + ((kt + 1) & 1) * 256 * LD;
;       u16* bw = Bs0 + ((kt + 1) & 1) * 256 * LD;
; #pragma unroll
;       for (int i = 0; i < 4; ++i) { *(u32x4*)(aw + (srow + 64 * i) * LD + skc * 8) = ra[i]; *(u32x4*)(bw + (srow + 64 * i) * LD + skc * 8) = rb[i]; }
;     }
;     if (kt + 2 < nk) {
; #pragma unroll
;       for (int i = 0; i < 4; ++i) { ra[i] = *(const u32x4*)(Ag + (size_t)(64 * i) * K + (kt + 2) * 64); rb[i] = *(const u32x4*)(Bg[i] + (kt + 2) * 64); }
;     }
;     __builtin_amdgcn_sched_barrier(0);
;     const u16* as = As0 + (kt & 1) * 256 * LD + (wr * 128 + l31) * LD + h * 8;
;     const u16* bs = Bs0 + (kt & 1) * 256 * LD + (wc * 64 + l31) * LD + h * 8;
;     if (domma)
; #pragma unroll
;     for (int ks = 0; ks < 4; ++ks) {
;       bf16x8 wf[2], xf[4];
; #pragma unroll
;       for (int ct = 0; ct < 2; ++ct) wf[ct] = *(const bf16x8*)(bs + ct * 32 * LD + ks * 16);
; #pragma unroll
;       for (int tt = 0; tt < 4; ++tt) xf[tt] = *(const bf16x8*)(as + tt * 32 * LD + ks * 16);
; #pragma unroll
;       for (int ct = 0; ct < 2; ++ct)
; #pragma unroll
;         for (int tt = 0; tt < 4; ++tt) acc[ct][tt] = __builtin_amdgcn_mfma_f32_32x32x16_bf16(wf[ct], xf[tt], acc[ct][tt], 0, 0, 0);
;     }
;     __builtin_amdgcn_sched_barrier(0);
;   }
	ds_read_b128 v[210:213], v249 offset:36864
	ds_read_b128 v[236:239], v248 offset:36864
	ds_read_b128 v[214:217], v249 offset:41472
	ds_read_b128 v[2:5], v248 offset:41472
	ds_read_b128 v[6:9], v248 offset:46080
	ds_read_b128 v[10:13], v248 offset:50688
	s_waitcnt lgkmcnt(4)
	v_mfma_f32_32x32x16_bf16 v[114:129], v[210:213], v[236:239], v[114:129]
	ds_read_b128 v[228:231], v249 offset:36896
	s_waitcnt lgkmcnt(4)
	v_mfma_f32_32x32x16_bf16 v[130:145], v[214:217], v[236:239], v[130:145]
	ds_read_b128 v[14:17], v248 offset:36896
	s_waitcnt lgkmcnt(4)
	v_mfma_f32_32x32x16_bf16 v[82:97], v[210:213], v[2:5], v[82:97]
	ds_read_b128 v[232:235], v249 offset:41504
	v_mfma_f32_32x32x16_bf16 v[98:113], v[214:217], v[2:5], v[98:113]
	ds_read_b128 v[236:239], v248 offset:41504
	s_waitcnt vmcnt(15)
	ds_write_b128 v250, v[146:149]
	s_waitcnt lgkmcnt(6)
	v_mfma_f32_32x32x16_bf16 v[50:65], v[210:213], v[6:9], v[50:65]
	ds_read_b128 v[2:5], v248 offset:46112
	v_mfma_f32_32x32x16_bf16 v[66:81], v[214:217], v[6:9], v[66:81]
	global_load_dwordx4 v[146:149], v227, s[74:75] offset:1536
	s_waitcnt lgkmcnt(6)
	v_mfma_f32_32x32x16_bf16 v[18:33], v[210:213], v[10:13], v[18:33]
	ds_read_b128 v[6:9], v248 offset:50720
	s_waitcnt vmcnt(15)
	ds_write_b128 v251, v[178:181]
	v_mfma_f32_32x32x16_bf16 v[34:49], v[214:217], v[10:13], v[34:49]
	s_waitcnt lgkmcnt(6)
	v_mfma_f32_32x32x16_bf16 v[114:129], v[228:231], v[14:17], v[114:129]
	ds_read_b128 v[210:213], v249 offset:36928
	global_load_dwordx4 v[178:181], v227, s[82:83] offset:1536
	s_waitcnt lgkmcnt(6)
	v_mfma_f32_32x32x16_bf16 v[130:145], v[232:235], v[14:17], v[130:145]
	ds_read_b128 v[10:13], v248 offset:36928
	s_waitcnt vmcnt(15)
	ds_write_b128 v250, v[150:153] offset:9216
	s_waitcnt lgkmcnt(7)
	v_mfma_f32_32x32x16_bf16 v[82:97], v[228:231], v[236:239], v[82:97]
	ds_read_b128 v[214:217], v249 offset:41536
	v_mfma_f32_32x32x16_bf16 v[98:113], v[232:235], v[236:239], v[98:113]
	ds_read_b128 v[14:17], v248 offset:41536
	global_load_dwordx4 v[150:153], v227, s[76:77] offset:1536
	s_waitcnt lgkmcnt(7)
	v_mfma_f32_32x32x16_bf16 v[50:65], v[228:231], v[2:5], v[50:65]
	ds_read_b128 v[236:239], v248 offset:46144
	s_waitcnt vmcnt(15)
	ds_write_b128 v251, v[182:185] offset:9216
	v_mfma_f32_32x32x16_bf16 v[66:81], v[232:235], v[2:5], v[66:81]
	s_waitcnt lgkmcnt(8)
	v_mfma_f32_32x32x16_bf16 v[18:33], v[228:231], v[6:9], v[18:33]
	ds_read_b128 v[2:5], v248 offset:50752
	global_load_dwordx4 v[182:185], v227, s[84:85] offset:1536
	v_mfma_f32_32x32x16_bf16 v[34:49], v[232:235], v[6:9], v[34:49]
	s_waitcnt vmcnt(15)
	ds_write_b128 v250, v[154:157] offset:18432
	s_waitcnt lgkmcnt(7)
	v_mfma_f32_32x32x16_bf16 v[114:129], v[210:213], v[10:13], v[114:129]
	ds_read_b128 v[228:231], v249 offset:36960
	s_waitcnt lgkmcnt(6)
	v_mfma_f32_32x32x16_bf16 v[130:145], v[214:217], v[10:13], v[130:145]
	ds_read_b128 v[6:9], v248 offset:36960
	global_load_dwordx4 v[154:157], v227, s[78:79] offset:1536
	s_waitcnt lgkmcnt(6)
	v_mfma_f32_32x32x16_bf16 v[82:97], v[210:213], v[14:17], v[82:97]
	ds_read_b128 v[232:235], v249 offset:41568
	s_waitcnt vmcnt(15)
	ds_write_b128 v251, v[186:189] offset:18432
	v_mfma_f32_32x32x16_bf16 v[98:113], v[214:217], v[14:17], v[98:113]
	ds_read_b128 v[10:13], v248 offset:41568
	s_waitcnt lgkmcnt(8)
	v_mfma_f32_32x32x16_bf16 v[50:65], v[210:213], v[236:239], v[50:65]
	ds_read_b128 v[14:17], v248 offset:46176
	global_load_dwordx4 v[186:189], v227, s[86:87] offset:1536
	v_mfma_f32_32x32x16_bf16 v[66:81], v[214:217], v[236:239], v[66:81]
	s_waitcnt vmcnt(15)
	ds_write_b128 v250, v[158:161] offset:27648
	s_waitcnt lgkmcnt(8)
	v_mfma_f32_32x32x16_bf16 v[18:33], v[210:213], v[2:5], v[18:33]
	ds_read_b128 v[236:239], v248 offset:50784
	v_mfma_f32_32x32x16_bf16 v[34:49], v[214:217], v[2:5], v[34:49]
	global_load_dwordx4 v[158:161], v227, s[80:81] offset:1536
	s_waitcnt lgkmcnt(6)
	v_mfma_f32_32x32x16_bf16 v[114:129], v[228:231], v[6:9], v[114:129]
	s_waitcnt vmcnt(15)
	ds_write_b128 v251, v[190:193] offset:27648
	s_waitcnt lgkmcnt(6)
	v_mfma_f32_32x32x16_bf16 v[130:145], v[232:235], v[6:9], v[130:145]
	s_waitcnt lgkmcnt(4)
	v_mfma_f32_32x32x16_bf16 v[82:97], v[228:231], v[10:13], v[82:97]
	global_load_dwordx4 v[190:193], v227, s[92:93] offset:1536
	v_mfma_f32_32x32x16_bf16 v[98:113], v[232:235], v[10:13], v[98:113]
	s_waitcnt lgkmcnt(3)
	v_mfma_f32_32x32x16_bf16 v[50:65], v[228:231], v[14:17], v[50:65]
	v_mfma_f32_32x32x16_bf16 v[66:81], v[232:235], v[14:17], v[66:81]
	s_waitcnt lgkmcnt(1)
	v_mfma_f32_32x32x16_bf16 v[18:33], v[228:231], v[236:239], v[18:33]
	v_mfma_f32_32x32x16_bf16 v[34:49], v[232:235], v[236:239], v[34:49]
	s_waitcnt lgkmcnt(0)
	s_barrier
;     ...
;   for (int kt = 0; kt < nk; ++kt) {
;     __syncthreads();
;     if (kt + 1 < nk) {
;       u16* aw = As0 + ((kt + 1) & 1) * 256 * LD;
;       u16* bw = Bs0 + ((kt + 1) & 1) * 256 * LD;
; #pragma unroll
;       for (int i = 0; i < 4; ++i) { *(u32x4*)(aw + (srow + 64 * i) * LD + skc * 8) = ra[i]; *(u32x4*)(bw + (srow + 64 * i) * LD + skc * 8) = rb[i]; }
;     }
;     if (kt + 2 < nk) {
; #pragma unroll
;       for (int i = 0; i < 4; ++i) { ra[i] = *(const u32x4*)(Ag + (size_t)(64 * i) * K + (kt + 2) * 64); rb[i] = *(const u32x4*)(Bg[i] + (kt + 2) * 64); }
;     }
;     __builtin_amdgcn_sched_barrier(0);
;     const u16* as = As0 + (kt & 1) * 256 * LD + (wr * 128 + l31) * LD + h * 8;
;     const u16* bs = Bs0 + (kt & 1) * 256 * LD + (wc * 64 + l31) * LD + h * 8;
;     if (domma)
; #pragma unroll
;     for (int ks = 0; ks < 4; ++ks) {
;       bf16x8 wf[2], xf[4];
; #pragma unroll
;       for (int ct = 0; ct < 2; ++ct) wf[ct] = *(const bf16x8*)(bs + ct * 32 * LD + ks * 16);
; #pragma unroll
;       for (int tt = 0; tt < 4; ++tt) xf[tt] = *(const bf16x8*)(as + tt * 32 * LD + ks * 16);
; #pragma unroll
;       for (int ct = 0; ct < 2; ++ct)
; #pragma unroll
;         for (int tt = 0; tt < 4; ++tt) acc[ct][tt] = __builtin_amdgcn_mfma_f32_32x32x16_bf16(wf[ct], xf[tt], acc[ct][tt], 0, 0, 0);
;     }
;     __builtin_amdgcn_sched_barrier(0);
;   }
	ds_read_b128 v[210:213], v249
	ds_read_b128 v[236:239], v248
	ds_read_b128 v[214:217], v249 offset:4608
	ds_read_b128 v[2:5], v248 offset:4608
	ds_read_b128 v[6:9], v248 offset:9216
	ds_read_b128 v[10:13], v248 offset:13824
	s_waitcnt lgkmcnt(4)
	v_mfma_f32_32x32x16_bf16 v[114:129], v[210:213], v[236:239], v[114:129]
	ds_read_b128 v[228:231], v249 offset:32
	s_waitcnt lgkmcnt(4)
	v_mfma_f32_32x32x16_bf16 v[130:145], v[214:217], v[236:239], v[130:145]
	ds_read_b128 v[14:17], v248 offset:32
	s_waitcnt lgkmcnt(4)
	v_mfma_f32_32x32x16_bf16 v[82:97], v[210:213], v[2:5], v[82:97]
	ds_read_b128 v[232:235], v249 offset:4640
	v_mfma_f32_32x32x16_bf16 v[98:113], v[214:217], v[2:5], v[98:113]
	ds_read_b128 v[236:239], v248 offset:4640
	s_waitcnt vmcnt(15)
	ds_write_b128 v250, v[162:165] offset:36864
	s_waitcnt lgkmcnt(6)
	v_mfma_f32_32x32x16_bf16 v[50:65], v[210:213], v[6:9], v[50:65]
	ds_read_b128 v[2:5], v248 offset:9248
	v_mfma_f32_32x32x16_bf16 v[66:81], v[214:217], v[6:9], v[66:81]
	global_load_dwordx4 v[162:165], v227, s[74:75] offset:1664
	s_waitcnt lgkmcnt(6)
	v_mfma_f32_32x32x16_bf16 v[18:33], v[210:213], v[10:13], v[18:33]
	ds_read_b128 v[6:9], v248 offset:13856
	s_waitcnt vmcnt(15)
	ds_write_b128 v251, v[194:197] offset:36864
	v_mfma_f32_32x32x16_bf16 v[34:49], v[214:217], v[10:13], v[34:49]
	s_waitcnt lgkmcnt(6)
	v_mfma_f32_32x32x16_bf16 v[114:129], v[228:231], v[14:17], v[114:129]
	ds_read_b128 v[210:213], v249 offset:64
	global_load_dwordx4 v[194:197], v227, s[82:83] offset:1664
	s_waitcnt lgkmcnt(6)
	v_mfma_f32_32x32x16_bf16 v[130:145], v[232:235], v[14:17], v[130:145]
	ds_read_b128 v[10:13], v248 offset:64
	s_waitcnt vmcnt(15)
	ds_write_b128 v250, v[166:169] offset:46080
	s_waitcnt lgkmcnt(7)
	v_mfma_f32_32x32x16_bf16 v[82:97], v[228:231], v[236:239], v[82:97]
	ds_read_b128 v[214:217], v249 offset:4672
	v_mfma_f32_32x32x16_bf16 v[98:113], v[232:235], v[236:239], v[98:113]
	ds_read_b128 v[14:17], v248 offset:4672
	global_load_dwordx4 v[166:169], v227, s[76:77] offset:1664
	s_waitcnt lgkmcnt(7)
	v_mfma_f32_32x32x16_bf16 v[50:65], v[228:231], v[2:5], v[50:65]
	ds_read_b128 v[236:239], v248 offset:9280
	s_waitcnt vmcnt(15)
	ds_write_b128 v251, v[198:201] offset:46080
	v_mfma_f32_32x32x16_bf16 v[66:81], v[232:235], v[2:5], v[66:81]
	s_waitcnt lgkmcnt(8)
	v_mfma_f32_32x32x16_bf16 v[18:33], v[228:231], v[6:9], v[18:33]
	ds_read_b128 v[2:5], v248 offset:13888
	global_load_dwordx4 v[198:201], v227, s[84:85] offset:1664
	v_mfma_f32_32x32x16_bf16 v[34:49], v[232:235], v[6:9], v[34:49]
	s_waitcnt vmcnt(15)
	ds_write_b128 v250, v[170:173] offset:55296
	s_waitcnt lgkmcnt(7)
	v_mfma_f32_32x32x16_bf16 v[114:129], v[210:213], v[10:13], v[114:129]
	ds_read_b128 v[228:231], v249 offset:96
	s_waitcnt lgkmcnt(6)
	v_mfma_f32_32x32x16_bf16 v[130:145], v[214:217], v[10:13], v[130:145]
	ds_read_b128 v[6:9], v248 offset:96
	global_load_dwordx4 v[170:173], v227, s[78:79] offset:1664
	s_waitcnt lgkmcnt(6)
	v_mfma_f32_32x32x16_bf16 v[82:97], v[210:213], v[14:17], v[82:97]
	ds_read_b128 v[232:235], v249 offset:4704
	s_waitcnt vmcnt(15)
	ds_write_b128 v251, v[202:205] offset:55296
	v_mfma_f32_32x32x16_bf16 v[98:113], v[214:217], v[14:17], v[98:113]
	ds_read_b128 v[10:13], v248 offset:4704
	s_waitcnt lgkmcnt(8)
	v_mfma_f32_32x32x16_bf16 v[50:65], v[210:213], v[236:239], v[50:65]
	ds_read_b128 v[14:17], v248 offset:9312
	global_load_dwordx4 v[202:205], v227, s[86:87] offset:1664
	v_mfma_f32_32x32x16_bf16 v[66:81], v[214:217], v[236:239], v[66:81]
	s_waitcnt vmcnt(15)
	ds_write_b128 v250, v[174:177] offset:64512
	s_waitcnt lgkmcnt(8)
	v_mfma_f32_32x32x16_bf16 v[18:33], v[210:213], v[2:5], v[18:33]
	ds_read_b128 v[236:239], v248 offset:13920
	v_mfma_f32_32x32x16_bf16 v[34:49], v[214:217], v[2:5], v[34:49]
	global_load_dwordx4 v[174:177], v227, s[80:81] offset:1664
	s_waitcnt lgkmcnt(6)
	v_mfma_f32_32x32x16_bf16 v[114:129], v[228:231], v[6:9], v[114:129]
	s_waitcnt vmcnt(15)
	ds_write_b128 v251, v[206:209] offset:64512
	s_waitcnt lgkmcnt(6)
	v_mfma_f32_32x32x16_bf16 v[130:145], v[232:235], v[6:9], v[130:145]
	s_waitcnt lgkmcnt(4)
	v_mfma_f32_32x32x16_bf16 v[82:97], v[228:231], v[10:13], v[82:97]
	global_load_dwordx4 v[206:209], v227, s[92:93] offset:1664
	v_mfma_f32_32x32x16_bf16 v[98:113], v[232:235], v[10:13], v[98:113]
	s_waitcnt lgkmcnt(3)
	v_mfma_f32_32x32x16_bf16 v[50:65], v[228:231], v[14:17], v[50:65]
	v_mfma_f32_32x32x16_bf16 v[66:81], v[232:235], v[14:17], v[66:81]
	s_waitcnt lgkmcnt(1)
	v_mfma_f32_32x32x16_bf16 v[18:33], v[228:231], v[236:239], v[18:33]
	v_mfma_f32_32x32x16_bf16 v[34:49], v[232:235], v[236:239], v[34:49]
	s_waitcnt lgkmcnt(0)
	s_barrier
;     ...
;   for (int kt = 0; kt < nk; ++kt) {
;     __syncthreads();
;     if (kt + 1 < nk) {
;       u16* aw = As0 + ((kt + 1) & 1) * 256 * LD;
;       u16* bw = Bs0 + ((kt + 1) & 1) * 256 * LD;
; #pragma unroll
;       for (int i = 0; i < 4; ++i) { *(u32x4*)(aw + (srow + 64 * i) * LD + skc * 8) = ra[i]; *(u32x4*)(bw + (srow + 64 * i) * LD + skc * 8) = rb[i]; }
;     }
;     if (kt + 2 < nk) {
; #pragma unroll
;       for (int i = 0; i < 4; ++i) { ra[i] = *(const u32x4*)(Ag + (size_t)(64 * i) * K + (kt + 2) * 64); rb[i] = *(const u32x4*)(Bg[i] + (kt + 2) * 64); }
;     }
;     __builtin_amdgcn_sched_barrier(0);
;     const u16* as = As0 + (kt & 1) * 256 * LD + (wr * 128 + l31) * LD + h * 8;
;     const u16* bs = Bs0 + (kt & 1) * 256 * LD + (wc * 64 + l31) * LD + h * 8;
;     if (domma)
; #pragma unroll
;     for (int ks = 0; ks < 4; ++ks) {
;       bf16x8 wf[2], xf[4];
; #pragma unroll
;       for (int ct = 0; ct < 2; ++ct) wf[ct] = *(const bf16x8*)(bs + ct * 32 * LD + ks * 16);
; #pragma unroll
;       for (int tt = 0; tt < 4; ++tt) xf[tt] = *(const bf16x8*)(as + tt * 32 * LD + ks * 16);
; #pragma unroll
;       for (int ct = 0; ct < 2; ++ct)
; #pragma unroll
;         for (int tt = 0; tt < 4; ++tt) acc[ct][tt] = __builtin_amdgcn_mfma_f32_32x32x16_bf16(wf[ct], xf[tt], acc[ct][tt], 0, 0, 0);
;     }
;     __builtin_amdgcn_sched_barrier(0);
;   }
	ds_read_b128 v[210:213], v249 offset:36864
	ds_read_b128 v[236:239], v248 offset:36864
	ds_read_b128 v[214:217], v249 offset:41472
	ds_read_b128 v[2:5], v248 offset:41472
	ds_read_b128 v[6:9], v248 offset:46080
	ds_read_b128 v[10:13], v248 offset:50688
	s_waitcnt lgkmcnt(4)
	v_mfma_f32_32x32x16_bf16 v[114:129], v[210:213], v[236:239], v[114:129]
	ds_read_b128 v[228:231], v249 offset:36896
	s_waitcnt lgkmcnt(4)
	v_mfma_f32_32x32x16_bf16 v[130:145], v[214:217], v[236:239], v[130:145]
	ds_read_b128 v[14:17], v248 offset:36896
	s_waitcnt lgkmcnt(4)
	v_mfma_f32_32x32x16_bf16 v[82:97], v[210:213], v[2:5], v[82:97]
	ds_read_b128 v[232:235], v249 offset:41504
	v_mfma_f32_32x32x16_bf16 v[98:113], v[214:217], v[2:5], v[98:113]
	ds_read_b128 v[236:239], v248 offset:41504
	s_waitcnt vmcnt(15)
	ds_write_b128 v250, v[146:149]
	s_waitcnt lgkmcnt(6)
	v_mfma_f32_32x32x16_bf16 v[50:65], v[210:213], v[6:9], v[50:65]
	ds_read_b128 v[2:5], v248 offset:46112
	v_mfma_f32_32x32x16_bf16 v[66:81], v[214:217], v[6:9], v[66:81]
	global_load_dwordx4 v[146:149], v227, s[74:75] offset:1792
	s_waitcnt lgkmcnt(6)
	v_mfma_f32_32x32x16_bf16 v[18:33], v[210:213], v[10:13], v[18:33]
	ds_read_b128 v[6:9], v248 offset:50720
	s_waitcnt vmcnt(15)
	ds_write_b128 v251, v[178:181]
	v_mfma_f32_32x32x16_bf16 v[34:49], v[214:217], v[10:13], v[34:49]
	s_waitcnt lgkmcnt(6)
	v_mfma_f32_32x32x16_bf16 v[114:129], v[228:231], v[14:17], v[114:129]
	ds_read_b128 v[210:213], v249 offset:36928
	global_load_dwordx4 v[178:181], v227, s[82:83] offset:1792
	s_waitcnt lgkmcnt(6)
	v_mfma_f32_32x32x16_bf16 v[130:145], v[232:235], v[14:17], v[130:145]
	ds_read_b128 v[10:13], v248 offset:36928
	s_waitcnt vmcnt(15)
	ds_write_b128 v250, v[150:153] offset:9216
	s_waitcnt lgkmcnt(7)
	v_mfma_f32_32x32x16_bf16 v[82:97], v[228:231], v[236:239], v[82:97]
	ds_read_b128 v[214:217], v249 offset:41536
	v_mfma_f32_32x32x16_bf16 v[98:113], v[232:235], v[236:239], v[98:113]
	ds_read_b128 v[14:17], v248 offset:41536
	global_load_dwordx4 v[150:153], v227, s[76:77] offset:1792
	s_waitcnt lgkmcnt(7)
	v_mfma_f32_32x32x16_bf16 v[50:65], v[228:231], v[2:5], v[50:65]
	ds_read_b128 v[236:239], v248 offset:46144
	s_waitcnt vmcnt(15)
	ds_write_b128 v251, v[182:185] offset:9216
	v_mfma_f32_32x32x16_bf16 v[66:81], v[232:235], v[2:5], v[66:81]
	s_waitcnt lgkmcnt(8)
	v_mfma_f32_32x32x16_bf16 v[18:33], v[228:231], v[6:9], v[18:33]
	ds_read_b128 v[2:5], v248 offset:50752
	global_load_dwordx4 v[182:185], v227, s[84:85] offset:1792
	v_mfma_f32_32x32x16_bf16 v[34:49], v[232:235], v[6:9], v[34:49]
	s_waitcnt vmcnt(15)
	ds_write_b128 v250, v[154:157] offset:18432
	s_waitcnt lgkmcnt(7)
	v_mfma_f32_32x32x16_bf16 v[114:129], v[210:213], v[10:13], v[114:129]
	ds_read_b128 v[228:231], v249 offset:36960
	s_waitcnt lgkmcnt(6)
	v_mfma_f32_32x32x16_bf16 v[130:145], v[214:217], v[10:13], v[130:145]
	ds_read_b128 v[6:9], v248 offset:36960
	global_load_dwordx4 v[154:157], v227, s[78:79] offset:1792
	s_waitcnt lgkmcnt(6)
	v_mfma_f32_32x32x16_bf16 v[82:97], v[210:213], v[14:17], v[82:97]
	ds_read_b128 v[232:235], v249 offset:41568
	s_waitcnt vmcnt(15)
	ds_write_b128 v251, v[186:189] offset:18432
	v_mfma_f32_32x32x16_bf16 v[98:113], v[214:217], v[14:17], v[98:113]
	ds_read_b128 v[10:13], v248 offset:41568
	s_waitcnt lgkmcnt(8)
	v_mfma_f32_32x32x16_bf16 v[50:65], v[210:213], v[236:239], v[50:65]
	ds_read_b128 v[14:17], v248 offset:46176
	global_load_dwordx4 v[186:189], v227, s[86:87] offset:1792
	v_mfma_f32_32x32x16_bf16 v[66:81], v[214:217], v[236:239], v[66:81]
	s_waitcnt vmcnt(15)
	ds_write_b128 v250, v[158:161] offset:27648
	s_waitcnt lgkmcnt(8)
	v_mfma_f32_32x32x16_bf16 v[18:33], v[210:213], v[2:5], v[18:33]
	ds_read_b128 v[236:239], v248 offset:50784
	v_mfma_f32_32x32x16_bf16 v[34:49], v[214:217], v[2:5], v[34:49]
	global_load_dwordx4 v[158:161], v227, s[80:81] offset:1792
	s_waitcnt lgkmcnt(6)
	v_mfma_f32_32x32x16_bf16 v[114:129], v[228:231], v[6:9], v[114:129]
	s_waitcnt vmcnt(15)
	ds_write_b128 v251, v[190:193] offset:27648
	s_waitcnt lgkmcnt(6)
	v_mfma_f32_32x32x16_bf16 v[130:145], v[232:235], v[6:9], v[130:145]
	s_waitcnt lgkmcnt(4)
	v_mfma_f32_32x32x16_bf16 v[82:97], v[228:231], v[10:13], v[82:97]
	global_load_dwordx4 v[190:193], v227, s[92:93] offset:1792
	v_mfma_f32_32x32x16_bf16 v[98:113], v[232:235], v[10:13], v[98:113]
	s_waitcnt lgkmcnt(3)
	v_mfma_f32_32x32x16_bf16 v[50:65], v[228:231], v[14:17], v[50:65]
	v_mfma_f32_32x32x16_bf16 v[66:81], v[232:235], v[14:17], v[66:81]
	s_waitcnt lgkmcnt(1)
	v_mfma_f32_32x32x16_bf16 v[18:33], v[228:231], v[236:239], v[18:33]
	v_mfma_f32_32x32x16_bf16 v[34:49], v[232:235], v[236:239], v[34:49]
	s_waitcnt lgkmcnt(0)
	s_barrier
;     ...
;   for (int kt = 0; kt < nk; ++kt) {
;     __syncthreads();
;     if (kt + 1 < nk) {
;       u16* aw = As0 + ((kt + 1) & 1) * 256 * LD;
;       u16* bw = Bs0 + ((kt + 1) & 1) * 256 * LD;
; #pragma unroll
;       for (int i = 0; i < 4; ++i) { *(u32x4*)(aw + (srow + 64 * i) * LD + skc * 8) = ra[i]; *(u32x4*)(bw + (srow + 64 * i) * LD + skc * 8) = rb[i]; }
;     }
;     if (kt + 2 < nk) {
; #pragma unroll
;       for (int i = 0; i < 4; ++i) { ra[i] = *(const u32x4*)(Ag + (size_t)(64 * i) * K + (kt + 2) * 64); rb[i] = *(const u32x4*)(Bg[i] + (kt + 2) * 64); }
;     }
;     __builtin_amdgcn_sched_barrier(0);
;     const u16* as = As0 + (kt & 1) * 256 * LD + (wr * 128 + l31) * LD + h * 8;
;     const u16* bs = Bs0 + (kt & 1) * 256 * LD + (wc * 64 + l31) * LD + h * 8;
;     if (domma)
; #pragma unroll
;     for (int ks = 0; ks < 4; ++ks) {
;       bf16x8 wf[2], xf[4];
; #pragma unroll
;       for (int ct = 0; ct < 2; ++ct) wf[ct] = *(const bf16x8*)(bs + ct * 32 * LD + ks * 16);
; #pragma unroll
;       for (int tt = 0; tt < 4; ++tt) xf[tt] = *(const bf16x8*)(as + tt * 32 * LD + ks * 16);
; #pragma unroll
;       for (int ct = 0; ct < 2; ++ct)
; #pragma unroll
;         for (int tt = 0; tt < 4; ++tt) acc[ct][tt] = __builtin_amdgcn_mfma_f32_32x32x16_bf16(wf[ct], xf[tt], acc[ct][tt], 0, 0, 0);
;     }
;     __builtin_amdgcn_sched_barrier(0);
;   }
	ds_read_b128 v[210:213], v249
	ds_read_b128 v[236:239], v248
	ds_read_b128 v[214:217], v249 offset:4608
	ds_read_b128 v[2:5], v248 offset:4608
	ds_read_b128 v[6:9], v248 offset:9216
	ds_read_b128 v[10:13], v248 offset:13824
	s_waitcnt lgkmcnt(4)
	v_mfma_f32_32x32x16_bf16 v[114:129], v[210:213], v[236:239], v[114:129]
	ds_read_b128 v[228:231], v249 offset:32
	s_waitcnt lgkmcnt(4)
	v_mfma_f32_32x32x16_bf16 v[130:145], v[214:217], v[236:239], v[130:145]
	ds_read_b128 v[14:17], v248 offset:32
	s_waitcnt lgkmcnt(4)
	v_mfma_f32_32x32x16_bf16 v[82:97], v[210:213], v[2:5], v[82:97]
	ds_read_b128 v[232:235], v249 offset:4640
	v_mfma_f32_32x32x16_bf16 v[98:113], v[214:217], v[2:5], v[98:113]
	ds_read_b128 v[236:239], v248 offset:4640
	s_waitcnt vmcnt(15)
	ds_write_b128 v250, v[162:165] offset:36864
	s_waitcnt lgkmcnt(6)
	v_mfma_f32_32x32x16_bf16 v[50:65], v[210:213], v[6:9], v[50:65]
	ds_read_b128 v[2:5], v248 offset:9248
	v_mfma_f32_32x32x16_bf16 v[66:81], v[214:217], v[6:9], v[66:81]
	global_load_dwordx4 v[162:165], v227, s[74:75] offset:1920
	s_waitcnt lgkmcnt(6)
	v_mfma_f32_32x32x16_bf16 v[18:33], v[210:213], v[10:13], v[18:33]
	ds_read_b128 v[6:9], v248 offset:13856
	s_waitcnt vmcnt(15)
	ds_write_b128 v251, v[194:197] offset:36864
	v_mfma_f32_32x32x16_bf16 v[34:49], v[214:217], v[10:13], v[34:49]
	s_waitcnt lgkmcnt(6)
	v_mfma_f32_32x32x16_bf16 v[114:129], v[228:231], v[14:17], v[114:129]
	ds_read_b128 v[210:213], v249 offset:64
	global_load_dwordx4 v[194:197], v227, s[82:83] offset:1920
	s_waitcnt lgkmcnt(6)
	v_mfma_f32_32x32x16_bf16 v[130:145], v[232:235], v[14:17], v[130:145]
	ds_read_b128 v[10:13], v248 offset:64
	s_waitcnt vmcnt(15)
	ds_write_b128 v250, v[166:169] offset:46080
	s_waitcnt lgkmcnt(7)
	v_mfma_f32_32x32x16_bf16 v[82:97], v[228:231], v[236:239], v[82:97]
	ds_read_b128 v[214:217], v249 offset:4672
	v_mfma_f32_32x32x16_bf16 v[98:113], v[232:235], v[236:239], v[98:113]
	ds_read_b128 v[14:17], v248 offset:4672
	global_load_dwordx4 v[166:169], v227, s[76:77] offset:1920
	s_waitcnt lgkmcnt(7)
	v_mfma_f32_32x32x16_bf16 v[50:65], v[228:231], v[2:5], v[50:65]
	ds_read_b128 v[236:239], v248 offset:9280
	s_waitcnt vmcnt(15)
	ds_write_b128 v251, v[198:201] offset:46080
	v_mfma_f32_32x32x16_bf16 v[66:81], v[232:235], v[2:5], v[66:81]
	s_waitcnt lgkmcnt(8)
	v_mfma_f32_32x32x16_bf16 v[18:33], v[228:231], v[6:9], v[18:33]
	ds_read_b128 v[2:5], v248 offset:13888
	global_load_dwordx4 v[198:201], v227, s[84:85] offset:1920
	v_mfma_f32_32x32x16_bf16 v[34:49], v[232:235], v[6:9], v[34:49]
	s_waitcnt vmcnt(15)
	ds_write_b128 v250, v[170:173] offset:55296
	s_waitcnt lgkmcnt(7)
	v_mfma_f32_32x32x16_bf16 v[114:129], v[210:213], v[10:13], v[114:129]
	ds_read_b128 v[228:231], v249 offset:96
	s_waitcnt lgkmcnt(6)
	v_mfma_f32_32x32x16_bf16 v[130:145], v[214:217], v[10:13], v[130:145]
	ds_read_b128 v[6:9], v248 offset:96
	global_load_dwordx4 v[170:173], v227, s[78:79] offset:1920
	s_waitcnt lgkmcnt(6)
	v_mfma_f32_32x32x16_bf16 v[82:97], v[210:213], v[14:17], v[82:97]
	ds_read_b128 v[232:235], v249 offset:4704
	s_waitcnt vmcnt(15)
	ds_write_b128 v251, v[202:205] offset:55296
	v_mfma_f32_32x32x16_bf16 v[98:113], v[214:217], v[14:17], v[98:113]
	ds_read_b128 v[10:13], v248 offset:4704
	s_waitcnt lgkmcnt(8)
	v_mfma_f32_32x32x16_bf16 v[50:65], v[210:213], v[236:239], v[50:65]
	ds_read_b128 v[14:17], v248 offset:9312
	global_load_dwordx4 v[202:205], v227, s[86:87] offset:1920
	v_mfma_f32_32x32x16_bf16 v[66:81], v[214:217], v[236:239], v[66:81]
	s_waitcnt vmcnt(15)
	ds_write_b128 v250, v[174:177] offset:64512
	s_waitcnt lgkmcnt(8)
	v_mfma_f32_32x32x16_bf16 v[18:33], v[210:213], v[2:5], v[18:33]
	ds_read_b128 v[236:239], v248 offset:13920
	v_mfma_f32_32x32x16_bf16 v[34:49], v[214:217], v[2:5], v[34:49]
	global_load_dwordx4 v[174:177], v227, s[80:81] offset:1920
	s_waitcnt lgkmcnt(6)
	v_mfma_f32_32x32x16_bf16 v[114:129], v[228:231], v[6:9], v[114:129]
	s_waitcnt vmcnt(15)
	ds_write_b128 v251, v[206:209] offset:64512
	s_waitcnt lgkmcnt(6)
	v_mfma_f32_32x32x16_bf16 v[130:145], v[232:235], v[6:9], v[130:145]
	s_waitcnt lgkmcnt(4)
	v_mfma_f32_32x32x16_bf16 v[82:97], v[228:231], v[10:13], v[82:97]
	global_load_dwordx4 v[206:209], v227, s[92:93] offset:1920
	v_mfma_f32_32x32x16_bf16 v[98:113], v[232:235], v[10:13], v[98:113]
	s_waitcnt lgkmcnt(3)
	v_mfma_f32_32x32x16_bf16 v[50:65], v[228:231], v[14:17], v[50:65]
	v_mfma_f32_32x32x16_bf16 v[66:81], v[232:235], v[14:17], v[66:81]
	s_waitcnt lgkmcnt(1)
	v_mfma_f32_32x32x16_bf16 v[18:33], v[228:231], v[236:239], v[18:33]
	v_mfma_f32_32x32x16_bf16 v[34:49], v[232:235], v[236:239], v[34:49]
	s_waitcnt lgkmcnt(0)
	s_barrier
;     ...
;   for (int kt = 0; kt < nk; ++kt) {
;     __syncthreads();
;     if (kt + 1 < nk) {
;       u16* aw = As0 + ((kt + 1) & 1) * 256 * LD;
;       u16* bw = Bs0 + ((kt + 1) & 1) * 256 * LD;
; #pragma unroll
;       for (int i = 0; i < 4; ++i) { *(u32x4*)(aw + (srow + 64 * i) * LD + skc * 8) = ra[i]; *(u32x4*)(bw + (srow + 64 * i) * LD + skc * 8) = rb[i]; }
;     }
;     if (kt + 2 < nk) {
; #pragma unroll
;       for (int i = 0; i < 4; ++i) { ra[i] = *(const u32x4*)(Ag + (size_t)(64 * i) * K + (kt + 2) * 64); rb[i] = *(const u32x4*)(Bg[i] + (kt + 2) * 64); }
;     }
;     __builtin_amdgcn_sched_barrier(0);
;     const u16* as = As0 + (kt & 1) * 256 * LD + (wr * 128 + l31) * LD + h * 8;
;     const u16* bs = Bs0 + (kt & 1) * 256 * LD + (wc * 64 + l31) * LD + h * 8;
;     if (domma)
; #pragma unroll
;     for (int ks = 0; ks < 4; ++ks) {
;       bf16x8 wf[2], xf[4];
; #pragma unroll
;       for (int ct = 0; ct < 2; ++ct) wf[ct] = *(const bf16x8*)(bs + ct * 32 * LD + ks * 16);
; #pragma unroll
;       for (int tt = 0; tt < 4; ++tt) xf[tt] = *(const bf16x8*)(as + tt * 32 * LD + ks * 16);
; #pragma unroll
;       for (int ct = 0; ct < 2; ++ct)
; #pragma unroll
;         for (int tt = 0; tt < 4; ++tt) acc[ct][tt] = __builtin_amdgcn_mfma_f32_32x32x16_bf16(wf[ct], xf[tt], acc[ct][tt], 0, 0, 0);
;     }
;     __builtin_amdgcn_sched_barrier(0);
;   }
	ds_read_b128 v[210:213], v249 offset:36864
	ds_read_b128 v[236:239], v248 offset:36864
	ds_read_b128 v[214:217], v249 offset:41472
	ds_read_b128 v[2:5], v248 offset:41472
	ds_read_b128 v[6:9], v248 offset:46080
	ds_read_b128 v[10:13], v248 offset:50688
	s_waitcnt lgkmcnt(4)
	v_mfma_f32_32x32x16_bf16 v[114:129], v[210:213], v[236:239], v[114:129]
	ds_read_b128 v[228:231], v249 offset:36896
	s_waitcnt lgkmcnt(4)
	v_mfma_f32_32x32x16_bf16 v[130:145], v[214:217], v[236:239], v[130:145]
	ds_read_b128 v[14:17], v248 offset:36896
	s_waitcnt lgkmcnt(4)
	v_mfma_f32_32x32x16_bf16 v[82:97], v[210:213], v[2:5], v[82:97]
	ds_read_b128 v[232:235], v249 offset:41504
	v_mfma_f32_32x32x16_bf16 v[98:113], v[214:217], v[2:5], v[98:113]
	ds_read_b128 v[236:239], v248 offset:41504
	s_waitcnt vmcnt(15)
	ds_write_b128 v250, v[146:149]
	s_waitcnt lgkmcnt(6)
	v_mfma_f32_32x32x16_bf16 v[50:65], v[210:213], v[6:9], v[50:65]
	ds_read_b128 v[2:5], v248 offset:46112
	v_mfma_f32_32x32x16_bf16 v[66:81], v[214:217], v[6:9], v[66:81]
	s_waitcnt lgkmcnt(6)
	v_mfma_f32_32x32x16_bf16 v[18:33], v[210:213], v[10:13], v[18:33]
	ds_read_b128 v[6:9], v248 offset:50720
	s_waitcnt vmcnt(14)
	ds_write_b128 v251, v[178:181]
	v_mfma_f32_32x32x16_bf16 v[34:49], v[214:217], v[10:13], v[34:49]
	s_waitcnt lgkmcnt(6)
	v_mfma_f32_32x32x16_bf16 v[114:129], v[228:231], v[14:17], v[114:129]
	ds_read_b128 v[210:213], v249 offset:36928
	s_waitcnt lgkmcnt(6)
	v_mfma_f32_32x32x16_bf16 v[130:145], v[232:235], v[14:17], v[130:145]
	ds_read_b128 v[10:13], v248 offset:36928
	s_waitcnt vmcnt(13)
	ds_write_b128 v250, v[150:153] offset:9216
	s_waitcnt lgkmcnt(7)
	v_mfma_f32_32x32x16_bf16 v[82:97], v[228:231], v[236:239], v[82:97]
	ds_read_b128 v[214:217], v249 offset:41536
	v_mfma_f32_32x32x16_bf16 v[98:113], v[232:235], v[236:239], v[98:113]
	ds_read_b128 v[14:17], v248 offset:41536
	s_waitcnt lgkmcnt(7)
	v_mfma_f32_32x32x16_bf16 v[50:65], v[228:231], v[2:5], v[50:65]
	ds_read_b128 v[236:239], v248 offset:46144
	s_waitcnt vmcnt(12)
	ds_write_b128 v251, v[182:185] offset:9216
	v_mfma_f32_32x32x16_bf16 v[66:81], v[232:235], v[2:5], v[66:81]
	s_waitcnt lgkmcnt(8)
	v_mfma_f32_32x32x16_bf16 v[18:33], v[228:231], v[6:9], v[18:33]
	ds_read_b128 v[2:5], v248 offset:50752
	v_mfma_f32_32x32x16_bf16 v[34:49], v[232:235], v[6:9], v[34:49]
	s_waitcnt vmcnt(11)
	ds_write_b128 v250, v[154:157] offset:18432
	s_waitcnt lgkmcnt(7)
	v_mfma_f32_32x32x16_bf16 v[114:129], v[210:213], v[10:13], v[114:129]
	ds_read_b128 v[228:231], v249 offset:36960
	s_waitcnt lgkmcnt(6)
	v_mfma_f32_32x32x16_bf16 v[130:145], v[214:217], v[10:13], v[130:145]
	ds_read_b128 v[6:9], v248 offset:36960
	s_waitcnt lgkmcnt(6)
	v_mfma_f32_32x32x16_bf16 v[82:97], v[210:213], v[14:17], v[82:97]
	ds_read_b128 v[232:235], v249 offset:41568
	s_waitcnt vmcnt(10)
	ds_write_b128 v251, v[186:189] offset:18432
	v_mfma_f32_32x32x16_bf16 v[98:113], v[214:217], v[14:17], v[98:113]
	ds_read_b128 v[10:13], v248 offset:41568
	s_waitcnt lgkmcnt(8)
	v_mfma_f32_32x32x16_bf16 v[50:65], v[210:213], v[236:239], v[50:65]
	ds_read_b128 v[14:17], v248 offset:46176
	v_mfma_f32_32x32x16_bf16 v[66:81], v[214:217], v[236:239], v[66:81]
	s_waitcnt vmcnt(9)
	ds_write_b128 v250, v[158:161] offset:27648
	s_waitcnt lgkmcnt(8)
	v_mfma_f32_32x32x16_bf16 v[18:33], v[210:213], v[2:5], v[18:33]
	ds_read_b128 v[236:239], v248 offset:50784
	v_mfma_f32_32x32x16_bf16 v[34:49], v[214:217], v[2:5], v[34:49]
	s_waitcnt lgkmcnt(6)
	v_mfma_f32_32x32x16_bf16 v[114:129], v[228:231], v[6:9], v[114:129]
	s_waitcnt vmcnt(8)
	ds_write_b128 v251, v[190:193] offset:27648
	s_waitcnt lgkmcnt(6)
	v_mfma_f32_32x32x16_bf16 v[130:145], v[232:235], v[6:9], v[130:145]
	s_waitcnt lgkmcnt(4)
	v_mfma_f32_32x32x16_bf16 v[82:97], v[228:231], v[10:13], v[82:97]
	v_mfma_f32_32x32x16_bf16 v[98:113], v[232:235], v[10:13], v[98:113]
	s_waitcnt lgkmcnt(3)
	v_mfma_f32_32x32x16_bf16 v[50:65], v[228:231], v[14:17], v[50:65]
	v_mfma_f32_32x32x16_bf16 v[66:81], v[232:235], v[14:17], v[66:81]
	s_waitcnt lgkmcnt(1)
	v_mfma_f32_32x32x16_bf16 v[18:33], v[228:231], v[236:239], v[18:33]
	v_mfma_f32_32x32x16_bf16 v[34:49], v[232:235], v[236:239], v[34:49]
	s_waitcnt lgkmcnt(0)
	s_barrier
	ds_read_b128 v[210:213], v249
	ds_read_b128 v[236:239], v248
	ds_read_b128 v[214:217], v249 offset:4608
	ds_read_b128 v[2:5], v248 offset:4608
	ds_read_b128 v[6:9], v248 offset:9216
	ds_read_b128 v[10:13], v248 offset:13824
	s_waitcnt lgkmcnt(4)
	v_mfma_f32_32x32x16_bf16 v[114:129], v[210:213], v[236:239], v[114:129]
	ds_read_b128 v[228:231], v249 offset:32
	s_waitcnt lgkmcnt(4)
	v_mfma_f32_32x32x16_bf16 v[130:145], v[214:217], v[236:239], v[130:145]
	ds_read_b128 v[14:17], v248 offset:32
	s_waitcnt lgkmcnt(4)
	v_mfma_f32_32x32x16_bf16 v[82:97], v[210:213], v[2:5], v[82:97]
	ds_read_b128 v[232:235], v249 offset:4640
	v_mfma_f32_32x32x16_bf16 v[98:113], v[214:217], v[2:5], v[98:113]
	ds_read_b128 v[236:239], v248 offset:4640
	s_waitcnt vmcnt(7)
	ds_write_b128 v250, v[162:165] offset:36864
	s_waitcnt lgkmcnt(6)
	v_mfma_f32_32x32x16_bf16 v[50:65], v[210:213], v[6:9], v[50:65]
	ds_read_b128 v[2:5], v248 offset:9248
	v_mfma_f32_32x32x16_bf16 v[66:81], v[214:217], v[6:9], v[66:81]
	s_waitcnt lgkmcnt(6)
	v_mfma_f32_32x32x16_bf16 v[18:33], v[210:213], v[10:13], v[18:33]
	ds_read_b128 v[6:9], v248 offset:13856
	s_waitcnt vmcnt(6)
	ds_write_b128 v251, v[194:197] offset:36864
	v_mfma_f32_32x32x16_bf16 v[34:49], v[214:217], v[10:13], v[34:49]
	s_waitcnt lgkmcnt(6)
	v_mfma_f32_32x32x16_bf16 v[114:129], v[228:231], v[14:17], v[114:129]
	ds_read_b128 v[210:213], v249 offset:64
	s_waitcnt lgkmcnt(6)
;     ...
;   for (int kt = 0; kt < nk; ++kt) {
;     __syncthreads();
;     if (kt + 1 < nk) {
;       u16* aw = As0 + ((kt + 1) & 1) * 256 * LD;
;       u16* bw = Bs0 + ((kt + 1) & 1) * 256 * LD;
; #pragma unroll
;       for (int i = 0; i < 4; ++i) { *(u32x4*)(aw + (srow + 64 * i) * LD + skc * 8) = ra[i]; *(u32x4*)(bw + (srow + 64 * i) * LD + skc * 8) = rb[i]; }
;     }
;     if (kt + 2 < nk) {
; #pragma unroll
;       for (int i = 0; i < 4; ++i) { ra[i] = *(const u32x4*)(Ag + (size_t)(64 * i) * K + (kt + 2) * 64); rb[i] = *(const u32x4*)(Bg[i] + (kt + 2) * 64); }
;     }
;     __builtin_amdgcn_sched_barrier(0);
;     const u16* as = As0 + (kt & 1) * 256 * LD + (wr * 128 + l31) * LD + h * 8;
;     const u16* bs = Bs0 + (kt & 1) * 256 * LD + (wc * 64 + l31) * LD + h * 8;
;     if (domma)
; #pragma unroll
;     for (int ks = 0; ks < 4; ++ks) {
;       bf16x8 wf[2], xf[4];
; #pragma unroll
;       for (int ct = 0; ct < 2; ++ct) wf[ct] = *(const bf16x8*)(bs + ct * 32 * LD + ks * 16);
; #pragma unroll
;       for (int tt = 0; tt < 4; ++tt) xf[tt] = *(const bf16x8*)(as + tt * 32 * LD + ks * 16);
; #pragma unroll
;       for (int ct = 0; ct < 2; ++ct)
; #pragma unroll
;         for (int tt = 0; tt < 4; ++tt) acc[ct][tt] = __builtin_amdgcn_mfma_f32_32x32x16_bf16(wf[ct], xf[tt], acc[ct][tt], 0, 0, 0);
;     }
;     __builtin_amdgcn_sched_barrier(0);
;   }
;   __syncthreads();
;     ...
;       for (int tt = 0; tt < 4; ++tt) { tok[tt] = m0 + wr * 128 + tt * 32 + l31; rsv[tt] = p.rs[tok[tt]]; }
	v_mfma_f32_32x32x16_bf16 v[130:145], v[232:235], v[14:17], v[130:145]
	ds_read_b128 v[10:13], v248 offset:64
	s_waitcnt vmcnt(5)
	ds_write_b128 v250, v[166:169] offset:46080
	s_waitcnt lgkmcnt(7)
	v_mfma_f32_32x32x16_bf16 v[82:97], v[228:231], v[236:239], v[82:97]
	ds_read_b128 v[214:217], v249 offset:4672
	v_mfma_f32_32x32x16_bf16 v[98:113], v[232:235], v[236:239], v[98:113]
	ds_read_b128 v[14:17], v248 offset:4672
	s_waitcnt lgkmcnt(7)
	v_mfma_f32_32x32x16_bf16 v[50:65], v[228:231], v[2:5], v[50:65]
	ds_read_b128 v[236:239], v248 offset:9280
	s_waitcnt vmcnt(4)
	ds_write_b128 v251, v[198:201] offset:46080
	v_mfma_f32_32x32x16_bf16 v[66:81], v[232:235], v[2:5], v[66:81]
	s_waitcnt lgkmcnt(8)
	v_mfma_f32_32x32x16_bf16 v[18:33], v[228:231], v[6:9], v[18:33]
	ds_read_b128 v[2:5], v248 offset:13888
	v_mfma_f32_32x32x16_bf16 v[34:49], v[232:235], v[6:9], v[34:49]
	s_waitcnt vmcnt(3)
	ds_write_b128 v250, v[170:173] offset:55296
	s_waitcnt lgkmcnt(7)
	v_mfma_f32_32x32x16_bf16 v[114:129], v[210:213], v[10:13], v[114:129]
	ds_read_b128 v[228:231], v249 offset:96
	s_waitcnt lgkmcnt(6)
	v_mfma_f32_32x32x16_bf16 v[130:145], v[214:217], v[10:13], v[130:145]
	ds_read_b128 v[6:9], v248 offset:96
	s_waitcnt lgkmcnt(6)
	v_mfma_f32_32x32x16_bf16 v[82:97], v[210:213], v[14:17], v[82:97]
	ds_read_b128 v[232:235], v249 offset:4704
	s_waitcnt vmcnt(2)
	ds_write_b128 v251, v[202:205] offset:55296
	v_mfma_f32_32x32x16_bf16 v[98:113], v[214:217], v[14:17], v[98:113]
	ds_read_b128 v[10:13], v248 offset:4704
	s_waitcnt lgkmcnt(8)
	v_mfma_f32_32x32x16_bf16 v[50:65], v[210:213], v[236:239], v[50:65]
	ds_read_b128 v[14:17], v248 offset:9312
	v_mfma_f32_32x32x16_bf16 v[66:81], v[214:217], v[236:239], v[66:81]
	s_waitcnt vmcnt(1)
	ds_write_b128 v250, v[174:177] offset:64512
	s_waitcnt lgkmcnt(8)
	v_mfma_f32_32x32x16_bf16 v[18:33], v[210:213], v[2:5], v[18:33]
	ds_read_b128 v[236:239], v248 offset:13920
	v_mfma_f32_32x32x16_bf16 v[34:49], v[214:217], v[2:5], v[34:49]
	s_waitcnt lgkmcnt(6)
	v_mfma_f32_32x32x16_bf16 v[114:129], v[228:231], v[6:9], v[114:129]
	s_waitcnt vmcnt(0)
	ds_write_b128 v251, v[206:209] offset:64512
	s_waitcnt lgkmcnt(6)
	v_mfma_f32_32x32x16_bf16 v[130:145], v[232:235], v[6:9], v[130:145]
	s_waitcnt lgkmcnt(4)
	v_mfma_f32_32x32x16_bf16 v[82:97], v[228:231], v[10:13], v[82:97]
	v_mfma_f32_32x32x16_bf16 v[98:113], v[232:235], v[10:13], v[98:113]
	s_waitcnt lgkmcnt(3)
	v_mfma_f32_32x32x16_bf16 v[50:65], v[228:231], v[14:17], v[50:65]
	v_mfma_f32_32x32x16_bf16 v[66:81], v[232:235], v[14:17], v[66:81]
	s_waitcnt lgkmcnt(1)
	v_mfma_f32_32x32x16_bf16 v[18:33], v[228:231], v[236:239], v[18:33]
	v_mfma_f32_32x32x16_bf16 v[34:49], v[232:235], v[236:239], v[34:49]
	s_waitcnt lgkmcnt(0)
	s_barrier
	ds_read_b128 v[210:213], v249 offset:36864
	ds_read_b128 v[236:239], v248 offset:36864
	ds_read_b128 v[214:217], v249 offset:41472
	ds_read_b128 v[2:5], v248 offset:41472
	ds_read_b128 v[6:9], v248 offset:46080
	ds_read_b128 v[10:13], v248 offset:50688
	s_waitcnt lgkmcnt(4)
	v_mfma_f32_32x32x16_bf16 v[114:129], v[210:213], v[236:239], v[114:129]
	ds_read_b128 v[228:231], v249 offset:36896
	s_waitcnt lgkmcnt(4)
	v_mfma_f32_32x32x16_bf16 v[130:145], v[214:217], v[236:239], v[130:145]
	ds_read_b128 v[14:17], v248 offset:36896
	s_waitcnt lgkmcnt(4)
	v_mfma_f32_32x32x16_bf16 v[82:97], v[210:213], v[2:5], v[82:97]
	ds_read_b128 v[232:235], v249 offset:41504
	v_mfma_f32_32x32x16_bf16 v[98:113], v[214:217], v[2:5], v[98:113]
	ds_read_b128 v[236:239], v248 offset:41504
	s_waitcnt lgkmcnt(5)
	v_mfma_f32_32x32x16_bf16 v[50:65], v[210:213], v[6:9], v[50:65]
	ds_read_b128 v[2:5], v248 offset:46112
	v_mfma_f32_32x32x16_bf16 v[66:81], v[214:217], v[6:9], v[66:81]
	s_waitcnt lgkmcnt(5)
	v_mfma_f32_32x32x16_bf16 v[18:33], v[210:213], v[10:13], v[18:33]
	ds_read_b128 v[6:9], v248 offset:50720
	v_mfma_f32_32x32x16_bf16 v[34:49], v[214:217], v[10:13], v[34:49]
	s_waitcnt lgkmcnt(4)
	v_mfma_f32_32x32x16_bf16 v[114:129], v[228:231], v[14:17], v[114:129]
	ds_read_b128 v[210:213], v249 offset:36928
	s_waitcnt lgkmcnt(4)
	v_mfma_f32_32x32x16_bf16 v[130:145], v[232:235], v[14:17], v[130:145]
	ds_read_b128 v[10:13], v248 offset:36928
	s_waitcnt lgkmcnt(4)
	v_mfma_f32_32x32x16_bf16 v[82:97], v[228:231], v[236:239], v[82:97]
	ds_read_b128 v[214:217], v249 offset:41536
	v_mfma_f32_32x32x16_bf16 v[98:113], v[232:235], v[236:239], v[98:113]
	ds_read_b128 v[14:17], v248 offset:41536
	s_waitcnt lgkmcnt(5)
	v_mfma_f32_32x32x16_bf16 v[50:65], v[228:231], v[2:5], v[50:65]
	ds_read_b128 v[236:239], v248 offset:46144
	v_mfma_f32_32x32x16_bf16 v[66:81], v[232:235], v[2:5], v[66:81]
	s_waitcnt lgkmcnt(5)
	v_mfma_f32_32x32x16_bf16 v[18:33], v[228:231], v[6:9], v[18:33]
	ds_read_b128 v[2:5], v248 offset:50752
	v_mfma_f32_32x32x16_bf16 v[34:49], v[232:235], v[6:9], v[34:49]
	s_waitcnt lgkmcnt(4)
	v_mfma_f32_32x32x16_bf16 v[114:129], v[210:213], v[10:13], v[114:129]
	ds_read_b128 v[228:231], v249 offset:36960
	s_waitcnt lgkmcnt(4)
	v_mfma_f32_32x32x16_bf16 v[130:145], v[214:217], v[10:13], v[130:145]
	ds_read_b128 v[6:9], v248 offset:36960
	s_waitcnt lgkmcnt(4)
	v_mfma_f32_32x32x16_bf16 v[82:97], v[210:213], v[14:17], v[82:97]
	ds_read_b128 v[232:235], v249 offset:41568
	v_mfma_f32_32x32x16_bf16 v[98:113], v[214:217], v[14:17], v[98:113]
	ds_read_b128 v[10:13], v248 offset:41568
	s_waitcnt lgkmcnt(5)
	v_mfma_f32_32x32x16_bf16 v[50:65], v[210:213], v[236:239], v[50:65]
	ds_read_b128 v[14:17], v248 offset:46176
	v_mfma_f32_32x32x16_bf16 v[66:81], v[214:217], v[236:239], v[66:81]
	s_waitcnt lgkmcnt(5)
	v_mfma_f32_32x32x16_bf16 v[18:33], v[210:213], v[2:5], v[18:33]
	ds_read_b128 v[236:239], v248 offset:50784
	v_mfma_f32_32x32x16_bf16 v[34:49], v[214:217], v[2:5], v[34:49]
	s_waitcnt lgkmcnt(4)
	v_mfma_f32_32x32x16_bf16 v[114:129], v[228:231], v[6:9], v[114:129]
	s_waitcnt lgkmcnt(3)
	v_mfma_f32_32x32x16_bf16 v[130:145], v[232:235], v[6:9], v[130:145]
	s_waitcnt lgkmcnt(2)
	v_mfma_f32_32x32x16_bf16 v[82:97], v[228:231], v[10:13], v[82:97]
	v_mfma_f32_32x32x16_bf16 v[98:113], v[232:235], v[10:13], v[98:113]
	s_waitcnt lgkmcnt(1)
	v_mfma_f32_32x32x16_bf16 v[50:65], v[228:231], v[14:17], v[50:65]
	v_mfma_f32_32x32x16_bf16 v[66:81], v[232:235], v[14:17], v[66:81]
	s_waitcnt lgkmcnt(0)
	v_mfma_f32_32x32x16_bf16 v[18:33], v[228:231], v[236:239], v[18:33]
	v_mfma_f32_32x32x16_bf16 v[34:49], v[232:235], v[236:239], v[34:49]
	v_mov_b32_e32 v3, 0
	v_mov_b32_e32 v227, v223
	s_setprio 0
	s_branch .LBB0_139
